# sp7 (down GEMM) residual+LN epilogue regenerated by hand as a software pipeline: loads one batch ahead in two rotating buffers, counted vmcnt waits that never drain stores
# baseline (speedup 1.0000x reference)
; #define PG8_STAGE(bufoff, gbase, voff) do { _Pragma("unroll") for (int _i = 0; _i < 2; ++_i) \
;         __builtin_amdgcn_global_load_lds((const unsigned*)((const char*)(gbase) + (size_t)_i * p64##voff + (v##voff##_)), (LAS unsigned*)(lds + (bufoff) + ldsw + _i * 8192), 16, 0, 0); } while (0)
; #define PG8_LDA(dst, b, h) do { _Pragma("unroll") for (int m = 0; m < 4; ++m) _Pragma("unroll") for (int k = 0; k < 2; ++k) dst[m][k] = *(const LAS bf16x8*)(lds + PG8_SA(b, h) + aoff + m * 2048 + k * 1024); } while (0)
; #define PG8_LDB(dst, b, h) do { _Pragma("unroll") for (int n = 0; n < 2; ++n) _Pragma("unroll") for (int k = 0; k < 2; ++k) dst[n][k] = *(const LAS bf16x8*)(lds + PG8_SB(b, h) + boff + n * 2048 + k * 1024); } while (0)
; #define PG8_MMA(ai, bj, At, Bt) do { __builtin_amdgcn_s_setprio(1); _Pragma("unroll") for (int m = 0; m < 4; ++m) _Pragma("unroll") for (int n = 0; n < 2; ++n) _Pragma("unroll") for (int k = 0; k < 2; ++k) \
;         acc[ai][bj][m][n] = __builtin_amdgcn_mfma_f32_16x16x32_bf16(Bt[n][k], At[m][k], acc[ai][bj][m][n], 0, 0, 0); __builtin_amdgcn_s_setprio(0); } while (0)
; #define PG8_WAIT_L(n) asm volatile("s_waitcnt lgkmcnt(" #n ")" ::: "memory")
; #define PG8_BAR __builtin_amdgcn_s_barrier()
; #define PG8_SCHED __builtin_amdgcn_sched_barrier(0)
; template <class Epi, class Sched>
; DI void gemm_phase(LAS unsigned char* lds, const Gemm g, const Sched& S, const Epi& E, const int tid) {
;     ...
;         for (int t = 0; t < nt; t += 2) {
;             const bool last = (t == nt - 2);
;             const char* a1 = cA + (size_t)(t + 1) * kstep;
;             const char* a2 = last ? nA : cA + (size_t)(t + 2) * kstep; const char* b2 = last ? nB : cB + (size_t)(t + 2) * kstep;
;             const char* a3 = a2 + kstep; const char* b3 = b2 + kstep;
;             PG8_LDB(B0, 0, 0); PG8_SCHED; PG8_LDA(At, 0, 0); PG8_STAGE(PG8_SA(1, 1), a1 + hstepA, offA);
;             PG8_WAIT_L(8); PG8_BAR; PG8_WAIT_L(0); PG8_MMA(0, 0, At, B0); PG8_BAR; PG8_SCHED;
;             PG8_LDB(B1, 0, 1); PG8_STAGE(PG8_SB(0, 0), b2, offB);
;             PG8_BAR; PG8_WAIT_L(0); PG8_MMA(0, 1, At, B1); PG8_BAR;
;             PG8_LDA(At, 0, 1); PG8_STAGE(PG8_SA(0, 0), a2, offA);
;             PG8_BAR; PG8_WAIT_L(0); PG8_MMA(1, 0, At, B0); PG8_BAR; PG8_SCHED;
.LBB0_28:
	s_add_u32 s69, s50, 0xfff00080
	s_addc_u32 s70, s51, -1
	s_add_i32 s74, 0, 0x10000
	v_add_u32_e32 v142, s74, v193
	ds_read_b128 v[130:133], v142
	ds_read_b128 v[134:137], v142 offset:1024
	ds_read_b128 v[138:141], v142 offset:2048
	ds_read_b128 v[142:145], v142 offset:3072
	s_cmp_eq_u32 s68, 60
	s_cselect_b32 s71, s45, s70
	s_cselect_b32 s70, s66, s69
	s_cselect_b32 s73, s43, s53
	s_cselect_b32 s72, s67, s52
	v_lshl_add_u64 v[180:181], s[50:51], 0, v[146:147]
	s_add_i32 m0, s57, 0xc000
	ds_read_b128 v[148:151], v212
	ds_read_b128 v[152:155], v212 offset:1024
	ds_read_b128 v[156:159], v212 offset:2048
	ds_read_b128 v[160:163], v212 offset:3072
	ds_read_b128 v[164:167], v212 offset:4096
	ds_read_b128 v[168:171], v212 offset:5120
	ds_read_b128 v[172:175], v212 offset:6144
	ds_read_b128 v[176:179], v212 offset:7168
	global_load_lds_dwordx4 v[180:181], off
	v_lshl_add_u64 v[180:181], v[180:181], 0, s[78:79]
	s_add_i32 m0, s57, 0xe000
	s_nop 0
	global_load_lds_dwordx4 v[180:181], off
	s_waitcnt lgkmcnt(8)
	s_barrier
	s_waitcnt lgkmcnt(0)
	s_setprio 1
	s_waitcnt lgkmcnt(0)
	v_mfma_f32_16x16x32_bf16 v[126:129], v[130:133], v[148:151], v[126:129]
	v_mfma_f32_16x16x32_bf16 v[110:113], v[138:141], v[148:151], v[110:113]
	v_mfma_f32_16x16x32_bf16 v[122:125], v[130:133], v[156:159], v[122:125]
	v_mfma_f32_16x16x32_bf16 v[106:109], v[138:141], v[156:159], v[106:109]
	v_mfma_f32_16x16x32_bf16 v[118:121], v[130:133], v[164:167], v[118:121]
	v_mfma_f32_16x16x32_bf16 v[102:105], v[138:141], v[164:167], v[102:105]
	v_mfma_f32_16x16x32_bf16 v[114:117], v[130:133], v[172:175], v[114:117]
	v_mfma_f32_16x16x32_bf16 v[98:101], v[138:141], v[172:175], v[98:101]
	v_mfma_f32_16x16x32_bf16 v[126:129], v[134:137], v[152:155], v[126:129]
	v_mfma_f32_16x16x32_bf16 v[110:113], v[142:145], v[152:155], v[110:113]
	v_mfma_f32_16x16x32_bf16 v[122:125], v[134:137], v[160:163], v[122:125]
	v_mfma_f32_16x16x32_bf16 v[106:109], v[142:145], v[160:163], v[106:109]
	v_mfma_f32_16x16x32_bf16 v[118:121], v[134:137], v[168:171], v[118:121]
	v_mfma_f32_16x16x32_bf16 v[102:105], v[142:145], v[168:171], v[102:105]
	v_mfma_f32_16x16x32_bf16 v[114:117], v[134:137], v[176:179], v[114:117]
	v_mfma_f32_16x16x32_bf16 v[98:101], v[142:145], v[176:179], v[98:101]
	s_setprio 0
	s_barrier
	s_add_i32 s69, 0, 0x14000
	v_add_u32_e32 v198, s69, v193
	ds_read_b128 v[180:183], v198
	ds_read_b128 v[184:187], v198 offset:1024
	ds_read_b128 v[188:191], v198 offset:2048
	ds_read_b128 v[214:217], v198 offset:3072
	v_lshl_add_u64 v[198:199], s[72:73], 0, v[0:1]
	s_add_i32 s72, s74, s56
	s_mov_b32 m0, s72
	v_lshl_add_u64 v[200:201], v[198:199], 0, s[78:79]
	global_load_lds_dwordx4 v[198:199], off
	s_add_i32 m0, s72, 0x2000
	s_mov_b64 s[72:73], 0x80080
	global_load_lds_dwordx4 v[200:201], off
	s_barrier
	s_waitcnt lgkmcnt(0)
	s_setprio 1
	s_waitcnt lgkmcnt(0)
	v_mfma_f32_16x16x32_bf16 v[94:97], v[180:183], v[148:151], v[94:97]
	v_mfma_f32_16x16x32_bf16 v[78:81], v[188:191], v[148:151], v[78:81]
	v_mfma_f32_16x16x32_bf16 v[90:93], v[180:183], v[156:159], v[90:93]
	v_mfma_f32_16x16x32_bf16 v[74:77], v[188:191], v[156:159], v[74:77]
	v_mfma_f32_16x16x32_bf16 v[86:89], v[180:183], v[164:167], v[86:89]
	v_mfma_f32_16x16x32_bf16 v[70:73], v[188:191], v[164:167], v[70:73]
	v_mfma_f32_16x16x32_bf16 v[82:85], v[180:183], v[172:175], v[82:85]
	v_mfma_f32_16x16x32_bf16 v[66:69], v[188:191], v[172:175], v[66:69]
	v_mfma_f32_16x16x32_bf16 v[94:97], v[184:187], v[152:155], v[94:97]
	v_mfma_f32_16x16x32_bf16 v[78:81], v[214:217], v[152:155], v[78:81]
	v_mfma_f32_16x16x32_bf16 v[90:93], v[184:187], v[160:163], v[90:93]
	v_mfma_f32_16x16x32_bf16 v[74:77], v[214:217], v[160:163], v[74:77]
	v_mfma_f32_16x16x32_bf16 v[86:89], v[184:187], v[168:171], v[86:89]
	v_mfma_f32_16x16x32_bf16 v[70:73], v[214:217], v[168:171], v[70:73]
	v_mfma_f32_16x16x32_bf16 v[82:85], v[184:187], v[176:179], v[82:85]
	v_mfma_f32_16x16x32_bf16 v[66:69], v[214:217], v[176:179], v[66:69]
	s_setprio 0
	s_mov_b32 m0, s57
	v_lshl_add_u64 v[200:201], s[70:71], 0, v[0:1]
	s_barrier
	ds_read_b128 v[148:151], v212 offset:16384
	ds_read_b128 v[152:155], v212 offset:17408
	ds_read_b128 v[156:159], v212 offset:18432
	ds_read_b128 v[160:163], v212 offset:19456
	ds_read_b128 v[164:167], v212 offset:20480
	ds_read_b128 v[168:171], v212 offset:21504
	ds_read_b128 v[172:175], v212 offset:22528
	ds_read_b128 v[176:179], v212 offset:23552
	global_load_lds_dwordx4 v[200:201], off
	v_lshl_add_u64 v[218:219], v[200:201], 0, s[78:79]
	s_mov_b32 m0, s58
	s_nop 0
	global_load_lds_dwordx4 v[218:219], off
	s_barrier
	s_waitcnt lgkmcnt(0)
	s_setprio 1
	s_waitcnt lgkmcnt(0)
	v_mfma_f32_16x16x32_bf16 v[62:65], v[130:133], v[148:151], v[62:65]
	v_mfma_f32_16x16x32_bf16 v[46:49], v[138:141], v[148:151], v[46:49]
	v_mfma_f32_16x16x32_bf16 v[58:61], v[130:133], v[156:159], v[58:61]
	v_mfma_f32_16x16x32_bf16 v[42:45], v[138:141], v[156:159], v[42:45]
	v_mfma_f32_16x16x32_bf16 v[54:57], v[130:133], v[164:167], v[54:57]
	v_mfma_f32_16x16x32_bf16 v[38:41], v[138:141], v[164:167], v[38:41]
	v_mfma_f32_16x16x32_bf16 v[50:53], v[130:133], v[172:175], v[50:53]
	v_mfma_f32_16x16x32_bf16 v[34:37], v[138:141], v[172:175], v[34:37]
	v_mfma_f32_16x16x32_bf16 v[62:65], v[134:137], v[152:155], v[62:65]
	v_mfma_f32_16x16x32_bf16 v[46:49], v[142:145], v[152:155], v[46:49]
	v_mfma_f32_16x16x32_bf16 v[58:61], v[134:137], v[160:163], v[58:61]
	v_mfma_f32_16x16x32_bf16 v[42:45], v[142:145], v[160:163], v[42:45]
	v_mfma_f32_16x16x32_bf16 v[54:57], v[134:137], v[168:171], v[54:57]
	v_mfma_f32_16x16x32_bf16 v[38:41], v[142:145], v[168:171], v[38:41]
	v_mfma_f32_16x16x32_bf16 v[50:53], v[134:137], v[176:179], v[50:53]
	v_mfma_f32_16x16x32_bf16 v[34:37], v[142:145], v[176:179], v[34:37]
	s_setprio 0
	s_barrier
; #define PG8_STAGE(bufoff, gbase, voff) do { _Pragma("unroll") for (int _i = 0; _i < 2; ++_i) \
;         __builtin_amdgcn_global_load_lds((const unsigned*)((const char*)(gbase) + (size_t)_i * p64##voff + (v##voff##_)), (LAS unsigned*)(lds + (bufoff) + ldsw + _i * 8192), 16, 0, 0); } while (0)
; #define PG8_LDA(dst, b, h) do { _Pragma("unroll") for (int m = 0; m < 4; ++m) _Pragma("unroll") for (int k = 0; k < 2; ++k) dst[m][k] = *(const LAS bf16x8*)(lds + PG8_SA(b, h) + aoff + m * 2048 + k * 1024); } while (0)
; #define PG8_LDB(dst, b, h) do { _Pragma("unroll") for (int n = 0; n < 2; ++n) _Pragma("unroll") for (int k = 0; k < 2; ++k) dst[n][k] = *(const LAS bf16x8*)(lds + PG8_SB(b, h) + boff + n * 2048 + k * 1024); } while (0)
; #define PG8_MMA(ai, bj, At, Bt) do { __builtin_amdgcn_s_setprio(1); _Pragma("unroll") for (int m = 0; m < 4; ++m) _Pragma("unroll") for (int n = 0; n < 2; ++n) _Pragma("unroll") for (int k = 0; k < 2; ++k) \
;         acc[ai][bj][m][n] = __builtin_amdgcn_mfma_f32_16x16x32_bf16(Bt[n][k], At[m][k], acc[ai][bj][m][n], 0, 0, 0); __builtin_amdgcn_s_setprio(0); } while (0)
; #define PG8_WAIT_V(n) asm volatile("s_waitcnt vmcnt(" #n ")" ::: "memory")
; #define PG8_WAIT_L(n) asm volatile("s_waitcnt lgkmcnt(" #n ")" ::: "memory")
; #define PG8_BAR __builtin_amdgcn_s_barrier()
; #define PG8_SCHED __builtin_amdgcn_sched_barrier(0)
; template <class Epi, class Sched>
; DI void gemm_phase(LAS unsigned char* lds, const Gemm g, const Sched& S, const Epi& E, const int tid) {
;     ...
;             PG8_STAGE(PG8_SB(0, 1), b2 + hstepB, offB);
;             PG8_WAIT_V(6); PG8_BAR; PG8_MMA(1, 1, At, B1); PG8_BAR;
;             PG8_LDB(B0, 1, 0); PG8_SCHED; PG8_LDA(At, 1, 0); PG8_STAGE(PG8_SA(0, 1), a2 + hstepA, offA);
;             PG8_WAIT_L(8); PG8_BAR; PG8_WAIT_L(0); PG8_MMA(0, 0, At, B0); PG8_BAR; PG8_SCHED;
;             PG8_LDB(B1, 1, 1); PG8_STAGE(PG8_SB(1, 0), b3, offB);
;             PG8_BAR; PG8_WAIT_L(0); PG8_MMA(0, 1, At, B1); PG8_BAR;
;             PG8_LDA(At, 1, 1); PG8_STAGE(PG8_SA(1, 0), a3, offA);
;             PG8_BAR; PG8_WAIT_L(0); PG8_MMA(1, 0, At, B0); PG8_BAR; PG8_SCHED;
	s_add_i32 s69, s69, s56
	v_lshl_add_u64 v[130:131], v[198:199], 0, s[76:77]
	s_mov_b32 m0, s69
	s_nop 0
	global_load_lds_dwordx4 v[130:131], off
	v_lshl_add_u64 v[130:131], v[198:199], 0, vcc
	s_add_i32 m0, s69, 0x2000
	s_nop 0
	global_load_lds_dwordx4 v[130:131], off
	s_waitcnt vmcnt(6)
	s_barrier
	s_setprio 1
	v_mfma_f32_16x16x32_bf16 v[30:33], v[180:183], v[148:151], v[30:33]
	v_mfma_f32_16x16x32_bf16 v[14:17], v[188:191], v[148:151], v[14:17]
	v_mfma_f32_16x16x32_bf16 v[26:29], v[180:183], v[156:159], v[26:29]
	v_mfma_f32_16x16x32_bf16 v[10:13], v[188:191], v[156:159], v[10:13]
	v_mfma_f32_16x16x32_bf16 v[22:25], v[180:183], v[164:167], v[22:25]
	v_mfma_f32_16x16x32_bf16 v[6:9], v[188:191], v[164:167], v[6:9]
	v_mfma_f32_16x16x32_bf16 v[18:21], v[180:183], v[172:175], v[18:21]
	v_mfma_f32_16x16x32_bf16 v[2:5], v[188:191], v[172:175], v[2:5]
	v_mfma_f32_16x16x32_bf16 v[30:33], v[184:187], v[152:155], v[30:33]
	v_mfma_f32_16x16x32_bf16 v[14:17], v[214:217], v[152:155], v[14:17]
	v_mfma_f32_16x16x32_bf16 v[26:29], v[184:187], v[160:163], v[26:29]
	v_mfma_f32_16x16x32_bf16 v[10:13], v[214:217], v[160:163], v[10:13]
	v_mfma_f32_16x16x32_bf16 v[22:25], v[184:187], v[168:171], v[22:25]
	v_mfma_f32_16x16x32_bf16 v[6:9], v[214:217], v[168:171], v[6:9]
	v_mfma_f32_16x16x32_bf16 v[18:21], v[184:187], v[176:179], v[18:21]
	v_mfma_f32_16x16x32_bf16 v[2:5], v[214:217], v[176:179], v[2:5]
	s_setprio 0
	s_add_i32 s69, 0, 0x18000
	v_add_u32_e32 v142, s69, v193
	s_barrier
	ds_read_b128 v[130:133], v142
	ds_read_b128 v[134:137], v142 offset:1024
	ds_read_b128 v[138:141], v142 offset:2048
	ds_read_b128 v[142:145], v142 offset:3072
	s_mov_b32 m0, s59
	v_lshl_add_u64 v[180:181], v[200:201], 0, s[76:77]
	ds_read_b128 v[148:151], v212 offset:32768
	ds_read_b128 v[152:155], v212 offset:33792
	ds_read_b128 v[156:159], v212 offset:34816
	ds_read_b128 v[160:163], v212 offset:35840
	ds_read_b128 v[164:167], v212 offset:36864
	ds_read_b128 v[168:171], v212 offset:37888
	ds_read_b128 v[172:175], v212 offset:38912
	ds_read_b128 v[176:179], v212 offset:39936
	global_load_lds_dwordx4 v[180:181], off
	v_lshl_add_u64 v[180:181], v[200:201], 0, vcc
	s_mov_b32 m0, s60
	s_nop 0
	global_load_lds_dwordx4 v[180:181], off
	s_waitcnt lgkmcnt(8)
	s_barrier
	s_waitcnt lgkmcnt(0)
	s_setprio 1
	s_waitcnt lgkmcnt(0)
	v_mfma_f32_16x16x32_bf16 v[126:129], v[130:133], v[148:151], v[126:129]
	v_mfma_f32_16x16x32_bf16 v[110:113], v[138:141], v[148:151], v[110:113]
	v_mfma_f32_16x16x32_bf16 v[122:125], v[130:133], v[156:159], v[122:125]
	v_mfma_f32_16x16x32_bf16 v[106:109], v[138:141], v[156:159], v[106:109]
	v_mfma_f32_16x16x32_bf16 v[118:121], v[130:133], v[164:167], v[118:121]
	v_mfma_f32_16x16x32_bf16 v[102:105], v[138:141], v[164:167], v[102:105]
	v_mfma_f32_16x16x32_bf16 v[114:117], v[130:133], v[172:175], v[114:117]
	v_mfma_f32_16x16x32_bf16 v[98:101], v[138:141], v[172:175], v[98:101]
	v_mfma_f32_16x16x32_bf16 v[126:129], v[134:137], v[152:155], v[126:129]
	v_mfma_f32_16x16x32_bf16 v[110:113], v[142:145], v[152:155], v[110:113]
	v_mfma_f32_16x16x32_bf16 v[122:125], v[134:137], v[160:163], v[122:125]
	v_mfma_f32_16x16x32_bf16 v[106:109], v[142:145], v[160:163], v[106:109]
	v_mfma_f32_16x16x32_bf16 v[118:121], v[134:137], v[168:171], v[118:121]
	v_mfma_f32_16x16x32_bf16 v[102:105], v[142:145], v[168:171], v[102:105]
	v_mfma_f32_16x16x32_bf16 v[114:117], v[134:137], v[176:179], v[114:117]
	v_mfma_f32_16x16x32_bf16 v[98:101], v[142:145], v[176:179], v[98:101]
	s_setprio 0
	s_barrier
	s_add_i32 s70, 0, 0x1c000
	s_add_i32 s69, s69, s56
	v_add_u32_e32 v213, s70, v193
	v_lshl_add_u64 v[218:219], v[198:199], 0, s[26:27]
	s_mov_b32 m0, s69
	ds_read_b128 v[180:183], v213
	ds_read_b128 v[184:187], v213 offset:1024
	ds_read_b128 v[188:191], v213 offset:2048
	ds_read_b128 v[214:217], v213 offset:3072
	global_load_lds_dwordx4 v[218:219], off
	v_lshl_add_u64 v[218:219], v[198:199], 0, s[72:73]
	s_add_i32 m0, s69, 0x2000
	s_nop 0
	global_load_lds_dwordx4 v[218:219], off
	s_barrier
	s_waitcnt lgkmcnt(0)
	s_setprio 1
	s_waitcnt lgkmcnt(0)
	v_mfma_f32_16x16x32_bf16 v[94:97], v[180:183], v[148:151], v[94:97]
	v_mfma_f32_16x16x32_bf16 v[78:81], v[188:191], v[148:151], v[78:81]
	v_mfma_f32_16x16x32_bf16 v[90:93], v[180:183], v[156:159], v[90:93]
	v_mfma_f32_16x16x32_bf16 v[74:77], v[188:191], v[156:159], v[74:77]
	v_mfma_f32_16x16x32_bf16 v[86:89], v[180:183], v[164:167], v[86:89]
	v_mfma_f32_16x16x32_bf16 v[70:73], v[188:191], v[164:167], v[70:73]
	v_mfma_f32_16x16x32_bf16 v[82:85], v[180:183], v[172:175], v[82:85]
	v_mfma_f32_16x16x32_bf16 v[66:69], v[188:191], v[172:175], v[66:69]
	v_mfma_f32_16x16x32_bf16 v[94:97], v[184:187], v[152:155], v[94:97]
	v_mfma_f32_16x16x32_bf16 v[78:81], v[214:217], v[152:155], v[78:81]
	v_mfma_f32_16x16x32_bf16 v[90:93], v[184:187], v[160:163], v[90:93]
	v_mfma_f32_16x16x32_bf16 v[74:77], v[214:217], v[160:163], v[74:77]
	v_mfma_f32_16x16x32_bf16 v[86:89], v[184:187], v[168:171], v[86:89]
	v_mfma_f32_16x16x32_bf16 v[70:73], v[214:217], v[168:171], v[70:73]
	v_mfma_f32_16x16x32_bf16 v[82:85], v[184:187], v[176:179], v[82:85]
	v_mfma_f32_16x16x32_bf16 v[66:69], v[214:217], v[176:179], v[66:69]
	s_setprio 0
	s_mov_b32 m0, s61
	v_lshl_add_u64 v[218:219], v[200:201], 0, s[26:27]
	s_barrier
	ds_read_b128 v[148:151], v212 offset:49152
	ds_read_b128 v[152:155], v212 offset:50176
	ds_read_b128 v[156:159], v212 offset:51200
	ds_read_b128 v[160:163], v212 offset:52224
	ds_read_b128 v[164:167], v212 offset:53248
	ds_read_b128 v[168:171], v212 offset:54272
	ds_read_b128 v[172:175], v212 offset:55296
	ds_read_b128 v[176:179], v212 offset:56320
	global_load_lds_dwordx4 v[218:219], off
	v_lshl_add_u64 v[200:201], v[200:201], 0, s[72:73]
	s_mov_b32 m0, s62
	s_mov_b64 s[72:73], 0x100080
	global_load_lds_dwordx4 v[200:201], off
	s_barrier
; #define RES_LOAD(k, s) do { _Pragma("unroll") for (int m = 0; m < 4; ++m) { const int row = row0 + ((k) >> 2) * HALF + m * 16; const size_t o = (size_t)row * 1024 + col0 + (((k) >> 1) & 1) * HALF + ((k) & 1) * 16; \
;             xv[s][m] = *(const f32x4*)(xin + o); if (HAS_T) tv[s][m] = *(const u32x2*)(T + o); if (LNX) sm[s][m] = *(const f32x2*)(stats + 2 * (size_t)row); } } while (0)
; #define PG8_STAGE(bufoff, gbase, voff) do { _Pragma("unroll") for (int _i = 0; _i < 2; ++_i) \
;         __builtin_amdgcn_global_load_lds((const unsigned*)((const char*)(gbase) + (size_t)_i * p64##voff + (v##voff##_)), (LAS unsigned*)(lds + (bufoff) + ldsw + _i * 8192), 16, 0, 0); } while (0)
; #define PG8_MMA(ai, bj, At, Bt) do { __builtin_amdgcn_s_setprio(1); _Pragma("unroll") for (int m = 0; m < 4; ++m) _Pragma("unroll") for (int n = 0; n < 2; ++n) _Pragma("unroll") for (int k = 0; k < 2; ++k) \
;         acc[ai][bj][m][n] = __builtin_amdgcn_mfma_f32_16x16x32_bf16(Bt[n][k], At[m][k], acc[ai][bj][m][n], 0, 0, 0); __builtin_amdgcn_s_setprio(0); } while (0)
; #define PG8_WAIT_V(n) asm volatile("s_waitcnt vmcnt(" #n ")" ::: "memory")
; #define PG8_WAIT_L(n) asm volatile("s_waitcnt lgkmcnt(" #n ")" ::: "memory")
; #define PG8_BAR __builtin_amdgcn_s_barrier()
; #define PG8_SCHED __builtin_amdgcn_sched_barrier(0)
;     DI void operator()(const f32x4 (&acc)[2][2][4][2], const Unit& u, int wr, int wc, int fr, int fq) const {
;         const int row0 = u.pm * BM + wr * 64 + fr, col0 = u.pn * BM + wc * 32 + 4 * fq;
;         const size_t o0 = (size_t)row0 * 1024 + col0;
;         f32x4 xv[2][4]; u32x2 tv[2][4]; f32x2 sm[2][4];
;     ...
; #pragma unroll
;         for (int k = 0; k < 8; ++k) {
;             RES_LOAD(k, k & 1);
;             const int ai = k >> 2, bj = (k >> 1) & 1, n = k & 1;
;             f32x4 gv = {1.f, 1.f, 1.f, 1.f}, bv = {0.f, 0.f, 0.f, 0.f};
;             if (LNX) { gv = *(const f32x4*)(lg + col0 + bj * HALF + n * 16); bv = *(const f32x4*)(lb + col0 + bj * HALF + n * 16); }
; template <class Epi, class Sched>
; DI void gemm_phase(LAS unsigned char* lds, const Gemm g, const Sched& S, const Epi& E, const int tid) {
;     ...
;             PG8_BAR; PG8_WAIT_L(0); PG8_MMA(1, 0, At, B0); PG8_BAR; PG8_SCHED;
;             PG8_STAGE(PG8_SB(1, 1), b3 + hstepB, offB);
;             PG8_WAIT_V(6); PG8_BAR; PG8_MMA(1, 1, At, B1); PG8_BAR;
	s_waitcnt lgkmcnt(0)
	s_setprio 1
	s_waitcnt lgkmcnt(0)
	v_mfma_f32_16x16x32_bf16 v[62:65], v[130:133], v[148:151], v[62:65]
	v_mfma_f32_16x16x32_bf16 v[46:49], v[138:141], v[148:151], v[46:49]
	v_mfma_f32_16x16x32_bf16 v[58:61], v[130:133], v[156:159], v[58:61]
	v_mfma_f32_16x16x32_bf16 v[42:45], v[138:141], v[156:159], v[42:45]
	v_mfma_f32_16x16x32_bf16 v[54:57], v[130:133], v[164:167], v[54:57]
	v_mfma_f32_16x16x32_bf16 v[38:41], v[138:141], v[164:167], v[38:41]
	v_mfma_f32_16x16x32_bf16 v[50:53], v[130:133], v[172:175], v[50:53]
	v_mfma_f32_16x16x32_bf16 v[34:37], v[138:141], v[172:175], v[34:37]
	v_mfma_f32_16x16x32_bf16 v[62:65], v[134:137], v[152:155], v[62:65]
	v_mfma_f32_16x16x32_bf16 v[46:49], v[142:145], v[152:155], v[46:49]
	v_mfma_f32_16x16x32_bf16 v[58:61], v[134:137], v[160:163], v[58:61]
	v_mfma_f32_16x16x32_bf16 v[42:45], v[142:145], v[160:163], v[42:45]
	v_mfma_f32_16x16x32_bf16 v[54:57], v[134:137], v[168:171], v[54:57]
	v_mfma_f32_16x16x32_bf16 v[38:41], v[142:145], v[168:171], v[38:41]
	v_mfma_f32_16x16x32_bf16 v[50:53], v[134:137], v[176:179], v[50:53]
	v_mfma_f32_16x16x32_bf16 v[34:37], v[142:145], v[176:179], v[34:37]
	s_setprio 0
	s_barrier
	s_add_i32 s69, s70, s56
	v_lshl_add_u64 v[130:131], v[198:199], 0, s[72:73]
	s_mov_b64 s[70:71], 0x180080
	s_mov_b32 m0, s69
	s_nop 0
	global_load_lds_dwordx4 v[130:131], off
	v_lshl_add_u64 v[130:131], v[198:199], 0, s[70:71]
	s_add_i32 m0, s69, 0x2000
	s_nop 0
	global_load_lds_dwordx4 v[130:131], off
	s_waitcnt vmcnt(6)
	s_barrier
	s_setprio 1
	v_mfma_f32_16x16x32_bf16 v[30:33], v[180:183], v[148:151], v[30:33]
	v_mfma_f32_16x16x32_bf16 v[14:17], v[188:191], v[148:151], v[14:17]
	v_mfma_f32_16x16x32_bf16 v[26:29], v[180:183], v[156:159], v[26:29]
	v_mfma_f32_16x16x32_bf16 v[10:13], v[188:191], v[156:159], v[10:13]
	v_mfma_f32_16x16x32_bf16 v[22:25], v[180:183], v[164:167], v[22:25]
	v_mfma_f32_16x16x32_bf16 v[6:9], v[188:191], v[164:167], v[6:9]
	v_mfma_f32_16x16x32_bf16 v[18:21], v[180:183], v[172:175], v[18:21]
	v_mfma_f32_16x16x32_bf16 v[2:5], v[188:191], v[172:175], v[2:5]
	v_mfma_f32_16x16x32_bf16 v[30:33], v[184:187], v[152:155], v[30:33]
	v_mfma_f32_16x16x32_bf16 v[14:17], v[214:217], v[152:155], v[14:17]
	v_mfma_f32_16x16x32_bf16 v[26:29], v[184:187], v[160:163], v[26:29]
	v_mfma_f32_16x16x32_bf16 v[10:13], v[214:217], v[160:163], v[10:13]
	v_mfma_f32_16x16x32_bf16 v[22:25], v[184:187], v[168:171], v[22:25]
	v_mfma_f32_16x16x32_bf16 v[6:9], v[214:217], v[168:171], v[6:9]
	v_mfma_f32_16x16x32_bf16 v[18:21], v[184:187], v[176:179], v[18:21]
	v_mfma_f32_16x16x32_bf16 v[2:5], v[214:217], v[176:179], v[2:5]
	s_setprio 0
	s_add_i32 s68, s68, 2
	s_add_u32 s50, s50, 0x100
	s_addc_u32 s51, s51, 0
	s_add_u32 s52, s52, 0x100
	s_addc_u32 s53, s53, 0
	s_cmp_gt_u32 s68, 61
	s_barrier
	s_cbranch_scc0 .LBB0_28
	v_lshl_add_u32 v130, s65, 8, v192
	v_lshl_or_b32 v131, s64, 8, v211
	v_readlane_b32 s50, v253, 26
	v_readlane_b32 s51, v253, 27
	v_readlane_b32 s52, v251, 1
	v_readlane_b32 s53, v251, 2
	v_lshlrev_b32_e32 v250, 2, v131
	v_add_u32_e32 v132, 0, v130
	v_lshl_add_u32 v230, v132, 12, v250
	v_add_u32_e32 v132, 16, v130
	v_lshl_add_u32 v231, v132, 12, v250
	v_add_u32_e32 v132, 32, v130
	v_lshl_add_u32 v244, v132, 12, v250
	v_add_u32_e32 v132, 48, v130
	v_lshl_add_u32 v245, v132, 12, v250
	v_add_u32_e32 v132, 128, v130
	v_lshl_add_u32 v246, v132, 12, v250
	v_add_u32_e32 v132, 144, v130
	v_lshl_add_u32 v247, v132, 12, v250
	v_add_u32_e32 v132, 160, v130
	v_lshl_add_u32 v248, v132, 12, v250
	v_add_u32_e32 v132, 176, v130
	v_lshl_add_u32 v249, v132, 12, v250
	s_mov_b32 s64, 0x3fb504f3
	global_load_dwordx4 v[130:133], v230, s[90:91]
	global_load_dwordx4 v[134:137], v231, s[90:91]
	global_load_dwordx4 v[138:141], v244, s[90:91]
	global_load_dwordx4 v[142:145], v245, s[90:91]
	v_lshrrev_b32_e32 v148, 1, v230
	v_lshrrev_b32_e32 v156, 9, v230
	v_and_b32_e32 v156, -8, v156
	v_lshrrev_b32_e32 v150, 1, v231
	v_lshrrev_b32_e32 v158, 9, v231
	v_and_b32_e32 v158, -8, v158
	v_lshrrev_b32_e32 v152, 1, v244
	v_lshrrev_b32_e32 v160, 9, v244
	v_and_b32_e32 v160, -8, v160
	v_lshrrev_b32_e32 v154, 1, v245
	v_lshrrev_b32_e32 v162, 9, v245
	v_and_b32_e32 v162, -8, v162
	global_load_dwordx2 v[148:149], v148, s[50:51]
	global_load_dwordx2 v[150:151], v150, s[50:51]
	global_load_dwordx2 v[152:153], v152, s[50:51]
	global_load_dwordx2 v[154:155], v154, s[50:51]
	global_load_dwordx2 v[156:157], v156, s[52:53]
	global_load_dwordx2 v[158:159], v158, s[52:53]
	global_load_dwordx2 v[160:161], v160, s[52:53]
	global_load_dwordx2 v[162:163], v162, s[52:53]
	global_load_dwordx4 v[164:167], v250, s[4:5]
	global_load_dwordx4 v[168:171], v250, s[40:41]
	global_load_dwordx4 v[172:175], v230, s[90:91] offset:64
	global_load_dwordx4 v[176:179], v231, s[90:91] offset:64
	global_load_dwordx4 v[180:183], v244, s[90:91] offset:64
	global_load_dwordx4 v[184:187], v245, s[90:91] offset:64
	v_lshrrev_b32_e32 v188, 1, v230
	v_lshrrev_b32_e32 v214, 9, v230
	v_and_b32_e32 v214, -8, v214
	v_lshrrev_b32_e32 v190, 1, v231
	v_lshrrev_b32_e32 v216, 9, v231
	v_and_b32_e32 v216, -8, v216
	v_lshrrev_b32_e32 v198, 1, v244
	v_lshrrev_b32_e32 v218, 9, v244
	v_and_b32_e32 v218, -8, v218
	v_lshrrev_b32_e32 v200, 1, v245
	v_lshrrev_b32_e32 v220, 9, v245
	v_and_b32_e32 v220, -8, v220
	global_load_dwordx2 v[188:189], v188, s[50:51] offset:32
	global_load_dwordx2 v[190:191], v190, s[50:51] offset:32
	global_load_dwordx2 v[198:199], v198, s[50:51] offset:32
	global_load_dwordx2 v[200:201], v200, s[50:51] offset:32
	global_load_dwordx2 v[214:215], v214, s[52:53]
	global_load_dwordx2 v[216:217], v216, s[52:53]
	global_load_dwordx2 v[218:219], v218, s[52:53]
	global_load_dwordx2 v[220:221], v220, s[52:53]
	global_load_dwordx4 v[222:225], v250, s[4:5] offset:64
	global_load_dwordx4 v[226:229], v250, s[40:41] offset:64
	s_waitcnt vmcnt(14)
; DI float bf_lo(unsigned w) { return __uint_as_float(w << 16); }
; DI float bf_hi(unsigned w) { return __uint_as_float(w & 0xFFFF0000u); }
; #define RES_LOAD(k, s) do { _Pragma("unroll") for (int m = 0; m < 4; ++m) { const int row = row0 + ((k) >> 2) * HALF + m * 16; const size_t o = (size_t)row * 1024 + col0 + (((k) >> 1) & 1) * HALF + ((k) & 1) * 16; \
;             xv[s][m] = *(const f32x4*)(xin + o); if (HAS_T) tv[s][m] = *(const u32x2*)(T + o); if (LNX) sm[s][m] = *(const f32x2*)(stats + 2 * (size_t)row); } } while (0)
;     DI void operator()(const f32x4 (&acc)[2][2][4][2], const Unit& u, int wr, int wc, int fr, int fq) const {
;     ...
; #pragma unroll
;         for (int k = 0; k < 8; ++k) {
;             RES_LOAD(k, k & 1);
;             const int ai = k >> 2, bj = (k >> 1) & 1, n = k & 1;
;             f32x4 gv = {1.f, 1.f, 1.f, 1.f}, bv = {0.f, 0.f, 0.f, 0.f};
;             if (LNX) { gv = *(const f32x4*)(lg + col0 + bj * HALF + n * 16); bv = *(const f32x4*)(lb + col0 + bj * HALF + n * 16); }
; #pragma unroll
;             for (int m = 0; m < 4; ++m) {
;                 const size_t o = o0 + (size_t)(ai * HALF + m * 16) * 1024 + bj * HALF + n * 16;
;                 f32x4 x = xv[k & 1][m];
;                 if (LNX) x = (x - sm[k & 1][m][0]) * sm[k & 1][m][1] * gv + bv;
;                 f32x4 r = acc[ai][bj][m][n] + x * ALPHA;
;                 if (HAS_T) { const u32x2 t = tv[k & 1][m]; r[0] += bf_lo(t.x); r[1] += bf_hi(t.x); r[2] += bf_lo(t.y); r[3] += bf_hi(t.y); }
;                 *(f32x4*)(y + o) = r;
;             }
;         }
	v_sub_f32_e32 v130, v130, v156
	v_sub_f32_e32 v131, v131, v156
	v_sub_f32_e32 v132, v132, v156
	v_sub_f32_e32 v133, v133, v156
	v_pk_mul_f32 v[130:131], v[156:157], v[130:131] op_sel:[1,0]
	v_pk_mul_f32 v[132:133], v[156:157], v[132:133] op_sel:[1,0]
	v_pk_fma_f32 v[130:131], v[130:131], v[164:165], v[168:169]
	v_pk_fma_f32 v[132:133], v[132:133], v[166:167], v[170:171]
	v_pk_fma_f32 v[126:127], v[130:131], s[64:65], v[126:127] op_sel_hi:[1,0,1]
	v_pk_fma_f32 v[128:129], v[132:133], s[64:65], v[128:129] op_sel_hi:[1,0,1]
	v_lshlrev_b32_e32 v130, 16, v148
	v_and_b32_e32 v131, 0xffff0000, v148
	v_lshlrev_b32_e32 v132, 16, v149
	v_and_b32_e32 v133, 0xffff0000, v149
	v_pk_add_f32 v[126:127], v[126:127], v[130:131]
	v_pk_add_f32 v[128:129], v[128:129], v[132:133]
	v_sub_f32_e32 v134, v134, v158
	v_sub_f32_e32 v135, v135, v158
	v_sub_f32_e32 v136, v136, v158
	v_sub_f32_e32 v137, v137, v158
	v_pk_mul_f32 v[134:135], v[158:159], v[134:135] op_sel:[1,0]
	v_pk_mul_f32 v[136:137], v[158:159], v[136:137] op_sel:[1,0]
	v_pk_fma_f32 v[134:135], v[134:135], v[164:165], v[168:169]
	v_pk_fma_f32 v[136:137], v[136:137], v[166:167], v[170:171]
	v_pk_fma_f32 v[122:123], v[134:135], s[64:65], v[122:123] op_sel_hi:[1,0,1]
	v_pk_fma_f32 v[124:125], v[136:137], s[64:65], v[124:125] op_sel_hi:[1,0,1]
	v_lshlrev_b32_e32 v134, 16, v150
	v_and_b32_e32 v135, 0xffff0000, v150
	v_lshlrev_b32_e32 v136, 16, v151
	v_and_b32_e32 v137, 0xffff0000, v151
	v_pk_add_f32 v[122:123], v[122:123], v[134:135]
	v_pk_add_f32 v[124:125], v[124:125], v[136:137]
	v_sub_f32_e32 v138, v138, v160
	v_sub_f32_e32 v139, v139, v160
	v_sub_f32_e32 v140, v140, v160
	v_sub_f32_e32 v141, v141, v160
	v_pk_mul_f32 v[138:139], v[160:161], v[138:139] op_sel:[1,0]
	v_pk_mul_f32 v[140:141], v[160:161], v[140:141] op_sel:[1,0]
	v_pk_fma_f32 v[138:139], v[138:139], v[164:165], v[168:169]
	v_pk_fma_f32 v[140:141], v[140:141], v[166:167], v[170:171]
	v_pk_fma_f32 v[118:119], v[138:139], s[64:65], v[118:119] op_sel_hi:[1,0,1]
	v_pk_fma_f32 v[120:121], v[140:141], s[64:65], v[120:121] op_sel_hi:[1,0,1]
	v_lshlrev_b32_e32 v138, 16, v152
	v_and_b32_e32 v139, 0xffff0000, v152
	v_lshlrev_b32_e32 v140, 16, v153
	v_and_b32_e32 v141, 0xffff0000, v153
	v_pk_add_f32 v[118:119], v[118:119], v[138:139]
	v_pk_add_f32 v[120:121], v[120:121], v[140:141]
	v_sub_f32_e32 v142, v142, v162
	v_sub_f32_e32 v143, v143, v162
	v_sub_f32_e32 v144, v144, v162
	v_sub_f32_e32 v145, v145, v162
	v_pk_mul_f32 v[142:143], v[162:163], v[142:143] op_sel:[1,0]
	v_pk_mul_f32 v[144:145], v[162:163], v[144:145] op_sel:[1,0]
	v_pk_fma_f32 v[142:143], v[142:143], v[164:165], v[168:169]
	v_pk_fma_f32 v[144:145], v[144:145], v[166:167], v[170:171]
	v_pk_fma_f32 v[114:115], v[142:143], s[64:65], v[114:115] op_sel_hi:[1,0,1]
	v_pk_fma_f32 v[116:117], v[144:145], s[64:65], v[116:117] op_sel_hi:[1,0,1]
	v_lshlrev_b32_e32 v142, 16, v154
	v_and_b32_e32 v143, 0xffff0000, v154
	v_lshlrev_b32_e32 v144, 16, v155
	v_and_b32_e32 v145, 0xffff0000, v155
	v_pk_add_f32 v[114:115], v[114:115], v[142:143]
	v_pk_add_f32 v[116:117], v[116:117], v[144:145]
	global_store_dwordx4 v230, v[126:129], s[90:91]
	global_store_dwordx4 v231, v[122:125], s[90:91]
	global_store_dwordx4 v244, v[118:121], s[90:91]
	global_store_dwordx4 v245, v[114:117], s[90:91]
	global_load_dwordx4 v[130:133], v230, s[90:91] offset:512
	global_load_dwordx4 v[134:137], v231, s[90:91] offset:512
	global_load_dwordx4 v[138:141], v244, s[90:91] offset:512
	global_load_dwordx4 v[142:145], v245, s[90:91] offset:512
	v_lshrrev_b32_e32 v148, 1, v230
	v_lshrrev_b32_e32 v156, 9, v230
	v_and_b32_e32 v156, -8, v156
	v_lshrrev_b32_e32 v150, 1, v231
	v_lshrrev_b32_e32 v158, 9, v231
	v_and_b32_e32 v158, -8, v158
	v_lshrrev_b32_e32 v152, 1, v244
	v_lshrrev_b32_e32 v160, 9, v244
	v_and_b32_e32 v160, -8, v160
	v_lshrrev_b32_e32 v154, 1, v245
	v_lshrrev_b32_e32 v162, 9, v245
	v_and_b32_e32 v162, -8, v162
	global_load_dwordx2 v[148:149], v148, s[50:51] offset:256
	global_load_dwordx2 v[150:151], v150, s[50:51] offset:256
	global_load_dwordx2 v[152:153], v152, s[50:51] offset:256
	global_load_dwordx2 v[154:155], v154, s[50:51] offset:256
	global_load_dwordx2 v[156:157], v156, s[52:53]
	global_load_dwordx2 v[158:159], v158, s[52:53]
	global_load_dwordx2 v[160:161], v160, s[52:53]
	global_load_dwordx2 v[162:163], v162, s[52:53]
	global_load_dwordx4 v[164:167], v250, s[4:5] offset:512
	global_load_dwordx4 v[168:171], v250, s[40:41] offset:512
	s_waitcnt vmcnt(18)
; DI float bf_lo(unsigned w) { return __uint_as_float(w << 16); }
; DI float bf_hi(unsigned w) { return __uint_as_float(w & 0xFFFF0000u); }
; #define RES_LOAD(k, s) do { _Pragma("unroll") for (int m = 0; m < 4; ++m) { const int row = row0 + ((k) >> 2) * HALF + m * 16; const size_t o = (size_t)row * 1024 + col0 + (((k) >> 1) & 1) * HALF + ((k) & 1) * 16; \
;             xv[s][m] = *(const f32x4*)(xin + o); if (HAS_T) tv[s][m] = *(const u32x2*)(T + o); if (LNX) sm[s][m] = *(const f32x2*)(stats + 2 * (size_t)row); } } while (0)
;     DI void operator()(const f32x4 (&acc)[2][2][4][2], const Unit& u, int wr, int wc, int fr, int fq) const {
;     ...
; #pragma unroll
;         for (int k = 0; k < 8; ++k) {
;             RES_LOAD(k, k & 1);
;             const int ai = k >> 2, bj = (k >> 1) & 1, n = k & 1;
;             f32x4 gv = {1.f, 1.f, 1.f, 1.f}, bv = {0.f, 0.f, 0.f, 0.f};
;             if (LNX) { gv = *(const f32x4*)(lg + col0 + bj * HALF + n * 16); bv = *(const f32x4*)(lb + col0 + bj * HALF + n * 16); }
; #pragma unroll
;             for (int m = 0; m < 4; ++m) {
;                 const size_t o = o0 + (size_t)(ai * HALF + m * 16) * 1024 + bj * HALF + n * 16;
;                 f32x4 x = xv[k & 1][m];
;                 if (LNX) x = (x - sm[k & 1][m][0]) * sm[k & 1][m][1] * gv + bv;
;                 f32x4 r = acc[ai][bj][m][n] + x * ALPHA;
;                 if (HAS_T) { const u32x2 t = tv[k & 1][m]; r[0] += bf_lo(t.x); r[1] += bf_hi(t.x); r[2] += bf_lo(t.y); r[3] += bf_hi(t.y); }
;                 *(f32x4*)(y + o) = r;
;             }
;         }
	v_sub_f32_e32 v172, v172, v214
	v_sub_f32_e32 v173, v173, v214
	v_sub_f32_e32 v174, v174, v214
	v_sub_f32_e32 v175, v175, v214
	v_pk_mul_f32 v[172:173], v[214:215], v[172:173] op_sel:[1,0]
	v_pk_mul_f32 v[174:175], v[214:215], v[174:175] op_sel:[1,0]
	v_pk_fma_f32 v[172:173], v[172:173], v[222:223], v[226:227]
	v_pk_fma_f32 v[174:175], v[174:175], v[224:225], v[228:229]
	v_pk_fma_f32 v[110:111], v[172:173], s[64:65], v[110:111] op_sel_hi:[1,0,1]
	v_pk_fma_f32 v[112:113], v[174:175], s[64:65], v[112:113] op_sel_hi:[1,0,1]
	v_lshlrev_b32_e32 v172, 16, v188
	v_and_b32_e32 v173, 0xffff0000, v188
	v_lshlrev_b32_e32 v174, 16, v189
	v_and_b32_e32 v175, 0xffff0000, v189
	v_pk_add_f32 v[110:111], v[110:111], v[172:173]
	v_pk_add_f32 v[112:113], v[112:113], v[174:175]
	v_sub_f32_e32 v176, v176, v216
	v_sub_f32_e32 v177, v177, v216
	v_sub_f32_e32 v178, v178, v216
	v_sub_f32_e32 v179, v179, v216
	v_pk_mul_f32 v[176:177], v[216:217], v[176:177] op_sel:[1,0]
	v_pk_mul_f32 v[178:179], v[216:217], v[178:179] op_sel:[1,0]
	v_pk_fma_f32 v[176:177], v[176:177], v[222:223], v[226:227]
	v_pk_fma_f32 v[178:179], v[178:179], v[224:225], v[228:229]
	v_pk_fma_f32 v[106:107], v[176:177], s[64:65], v[106:107] op_sel_hi:[1,0,1]
	v_pk_fma_f32 v[108:109], v[178:179], s[64:65], v[108:109] op_sel_hi:[1,0,1]
	v_lshlrev_b32_e32 v176, 16, v190
	v_and_b32_e32 v177, 0xffff0000, v190
	v_lshlrev_b32_e32 v178, 16, v191
	v_and_b32_e32 v179, 0xffff0000, v191
	v_pk_add_f32 v[106:107], v[106:107], v[176:177]
	v_pk_add_f32 v[108:109], v[108:109], v[178:179]
	v_sub_f32_e32 v180, v180, v218
	v_sub_f32_e32 v181, v181, v218
	v_sub_f32_e32 v182, v182, v218
	v_sub_f32_e32 v183, v183, v218
	v_pk_mul_f32 v[180:181], v[218:219], v[180:181] op_sel:[1,0]
	v_pk_mul_f32 v[182:183], v[218:219], v[182:183] op_sel:[1,0]
	v_pk_fma_f32 v[180:181], v[180:181], v[222:223], v[226:227]
	v_pk_fma_f32 v[182:183], v[182:183], v[224:225], v[228:229]
	v_pk_fma_f32 v[102:103], v[180:181], s[64:65], v[102:103] op_sel_hi:[1,0,1]
	v_pk_fma_f32 v[104:105], v[182:183], s[64:65], v[104:105] op_sel_hi:[1,0,1]
	v_lshlrev_b32_e32 v180, 16, v198
	v_and_b32_e32 v181, 0xffff0000, v198
	v_lshlrev_b32_e32 v182, 16, v199
	v_and_b32_e32 v183, 0xffff0000, v199
	v_pk_add_f32 v[102:103], v[102:103], v[180:181]
	v_pk_add_f32 v[104:105], v[104:105], v[182:183]
	v_sub_f32_e32 v184, v184, v220
	v_sub_f32_e32 v185, v185, v220
	v_sub_f32_e32 v186, v186, v220
	v_sub_f32_e32 v187, v187, v220
	v_pk_mul_f32 v[184:185], v[220:221], v[184:185] op_sel:[1,0]
	v_pk_mul_f32 v[186:187], v[220:221], v[186:187] op_sel:[1,0]
	v_pk_fma_f32 v[184:185], v[184:185], v[222:223], v[226:227]
	v_pk_fma_f32 v[186:187], v[186:187], v[224:225], v[228:229]
	v_pk_fma_f32 v[98:99], v[184:185], s[64:65], v[98:99] op_sel_hi:[1,0,1]
	v_pk_fma_f32 v[100:101], v[186:187], s[64:65], v[100:101] op_sel_hi:[1,0,1]
	v_lshlrev_b32_e32 v184, 16, v200
	v_and_b32_e32 v185, 0xffff0000, v200
	v_lshlrev_b32_e32 v186, 16, v201
	v_and_b32_e32 v187, 0xffff0000, v201
	v_pk_add_f32 v[98:99], v[98:99], v[184:185]
	v_pk_add_f32 v[100:101], v[100:101], v[186:187]
	global_store_dwordx4 v230, v[110:113], s[90:91] offset:64
	global_store_dwordx4 v231, v[106:109], s[90:91] offset:64
	global_store_dwordx4 v244, v[102:105], s[90:91] offset:64
	global_store_dwordx4 v245, v[98:101], s[90:91] offset:64
	global_load_dwordx4 v[172:175], v230, s[90:91] offset:576
	global_load_dwordx4 v[176:179], v231, s[90:91] offset:576
	global_load_dwordx4 v[180:183], v244, s[90:91] offset:576
	global_load_dwordx4 v[184:187], v245, s[90:91] offset:576
	v_lshrrev_b32_e32 v188, 1, v230
	v_lshrrev_b32_e32 v214, 9, v230
	v_and_b32_e32 v214, -8, v214
	v_lshrrev_b32_e32 v190, 1, v231
	v_lshrrev_b32_e32 v216, 9, v231
	v_and_b32_e32 v216, -8, v216
	v_lshrrev_b32_e32 v198, 1, v244
	v_lshrrev_b32_e32 v218, 9, v244
	v_and_b32_e32 v218, -8, v218
	v_lshrrev_b32_e32 v200, 1, v245
	v_lshrrev_b32_e32 v220, 9, v245
	v_and_b32_e32 v220, -8, v220
	global_load_dwordx2 v[188:189], v188, s[50:51] offset:288
	global_load_dwordx2 v[190:191], v190, s[50:51] offset:288
	global_load_dwordx2 v[198:199], v198, s[50:51] offset:288
	global_load_dwordx2 v[200:201], v200, s[50:51] offset:288
	global_load_dwordx2 v[214:215], v214, s[52:53]
	global_load_dwordx2 v[216:217], v216, s[52:53]
	global_load_dwordx2 v[218:219], v218, s[52:53]
	global_load_dwordx2 v[220:221], v220, s[52:53]
	global_load_dwordx4 v[222:225], v250, s[4:5] offset:576
	global_load_dwordx4 v[226:229], v250, s[40:41] offset:576
	s_waitcnt vmcnt(18)
; DI float bf_lo(unsigned w) { return __uint_as_float(w << 16); }
; DI float bf_hi(unsigned w) { return __uint_as_float(w & 0xFFFF0000u); }
; #define RES_LOAD(k, s) do { _Pragma("unroll") for (int m = 0; m < 4; ++m) { const int row = row0 + ((k) >> 2) * HALF + m * 16; const size_t o = (size_t)row * 1024 + col0 + (((k) >> 1) & 1) * HALF + ((k) & 1) * 16; \
;             xv[s][m] = *(const f32x4*)(xin + o); if (HAS_T) tv[s][m] = *(const u32x2*)(T + o); if (LNX) sm[s][m] = *(const f32x2*)(stats + 2 * (size_t)row); } } while (0)
;     DI void operator()(const f32x4 (&acc)[2][2][4][2], const Unit& u, int wr, int wc, int fr, int fq) const {
;     ...
; #pragma unroll
;         for (int k = 0; k < 8; ++k) {
;             RES_LOAD(k, k & 1);
;             const int ai = k >> 2, bj = (k >> 1) & 1, n = k & 1;
;             f32x4 gv = {1.f, 1.f, 1.f, 1.f}, bv = {0.f, 0.f, 0.f, 0.f};
;             if (LNX) { gv = *(const f32x4*)(lg + col0 + bj * HALF + n * 16); bv = *(const f32x4*)(lb + col0 + bj * HALF + n * 16); }
; #pragma unroll
;             for (int m = 0; m < 4; ++m) {
;                 const size_t o = o0 + (size_t)(ai * HALF + m * 16) * 1024 + bj * HALF + n * 16;
;                 f32x4 x = xv[k & 1][m];
;                 if (LNX) x = (x - sm[k & 1][m][0]) * sm[k & 1][m][1] * gv + bv;
;                 f32x4 r = acc[ai][bj][m][n] + x * ALPHA;
;                 if (HAS_T) { const u32x2 t = tv[k & 1][m]; r[0] += bf_lo(t.x); r[1] += bf_hi(t.x); r[2] += bf_lo(t.y); r[3] += bf_hi(t.y); }
;                 *(f32x4*)(y + o) = r;
;             }
;         }
	v_sub_f32_e32 v130, v130, v156
	v_sub_f32_e32 v131, v131, v156
	v_sub_f32_e32 v132, v132, v156
	v_sub_f32_e32 v133, v133, v156
	v_pk_mul_f32 v[130:131], v[156:157], v[130:131] op_sel:[1,0]
	v_pk_mul_f32 v[132:133], v[156:157], v[132:133] op_sel:[1,0]
	v_pk_fma_f32 v[130:131], v[130:131], v[164:165], v[168:169]
	v_pk_fma_f32 v[132:133], v[132:133], v[166:167], v[170:171]
	v_pk_fma_f32 v[94:95], v[130:131], s[64:65], v[94:95] op_sel_hi:[1,0,1]
	v_pk_fma_f32 v[96:97], v[132:133], s[64:65], v[96:97] op_sel_hi:[1,0,1]
	v_lshlrev_b32_e32 v130, 16, v148
	v_and_b32_e32 v131, 0xffff0000, v148
	v_lshlrev_b32_e32 v132, 16, v149
	v_and_b32_e32 v133, 0xffff0000, v149
	v_pk_add_f32 v[94:95], v[94:95], v[130:131]
	v_pk_add_f32 v[96:97], v[96:97], v[132:133]
	v_sub_f32_e32 v134, v134, v158
	v_sub_f32_e32 v135, v135, v158
	v_sub_f32_e32 v136, v136, v158
	v_sub_f32_e32 v137, v137, v158
	v_pk_mul_f32 v[134:135], v[158:159], v[134:135] op_sel:[1,0]
	v_pk_mul_f32 v[136:137], v[158:159], v[136:137] op_sel:[1,0]
	v_pk_fma_f32 v[134:135], v[134:135], v[164:165], v[168:169]
	v_pk_fma_f32 v[136:137], v[136:137], v[166:167], v[170:171]
	v_pk_fma_f32 v[90:91], v[134:135], s[64:65], v[90:91] op_sel_hi:[1,0,1]
	v_pk_fma_f32 v[92:93], v[136:137], s[64:65], v[92:93] op_sel_hi:[1,0,1]
	v_lshlrev_b32_e32 v134, 16, v150
	v_and_b32_e32 v135, 0xffff0000, v150
	v_lshlrev_b32_e32 v136, 16, v151
	v_and_b32_e32 v137, 0xffff0000, v151
	v_pk_add_f32 v[90:91], v[90:91], v[134:135]
	v_pk_add_f32 v[92:93], v[92:93], v[136:137]
	v_sub_f32_e32 v138, v138, v160
	v_sub_f32_e32 v139, v139, v160
	v_sub_f32_e32 v140, v140, v160
	v_sub_f32_e32 v141, v141, v160
	v_pk_mul_f32 v[138:139], v[160:161], v[138:139] op_sel:[1,0]
	v_pk_mul_f32 v[140:141], v[160:161], v[140:141] op_sel:[1,0]
	v_pk_fma_f32 v[138:139], v[138:139], v[164:165], v[168:169]
	v_pk_fma_f32 v[140:141], v[140:141], v[166:167], v[170:171]
	v_pk_fma_f32 v[86:87], v[138:139], s[64:65], v[86:87] op_sel_hi:[1,0,1]
	v_pk_fma_f32 v[88:89], v[140:141], s[64:65], v[88:89] op_sel_hi:[1,0,1]
	v_lshlrev_b32_e32 v138, 16, v152
	v_and_b32_e32 v139, 0xffff0000, v152
	v_lshlrev_b32_e32 v140, 16, v153
	v_and_b32_e32 v141, 0xffff0000, v153
	v_pk_add_f32 v[86:87], v[86:87], v[138:139]
	v_pk_add_f32 v[88:89], v[88:89], v[140:141]
	v_sub_f32_e32 v142, v142, v162
	v_sub_f32_e32 v143, v143, v162
	v_sub_f32_e32 v144, v144, v162
	v_sub_f32_e32 v145, v145, v162
	v_pk_mul_f32 v[142:143], v[162:163], v[142:143] op_sel:[1,0]
	v_pk_mul_f32 v[144:145], v[162:163], v[144:145] op_sel:[1,0]
	v_pk_fma_f32 v[142:143], v[142:143], v[164:165], v[168:169]
	v_pk_fma_f32 v[144:145], v[144:145], v[166:167], v[170:171]
	v_pk_fma_f32 v[82:83], v[142:143], s[64:65], v[82:83] op_sel_hi:[1,0,1]
	v_pk_fma_f32 v[84:85], v[144:145], s[64:65], v[84:85] op_sel_hi:[1,0,1]
	v_lshlrev_b32_e32 v142, 16, v154
	v_and_b32_e32 v143, 0xffff0000, v154
	v_lshlrev_b32_e32 v144, 16, v155
	v_and_b32_e32 v145, 0xffff0000, v155
	v_pk_add_f32 v[82:83], v[82:83], v[142:143]
	v_pk_add_f32 v[84:85], v[84:85], v[144:145]
	global_store_dwordx4 v230, v[94:97], s[90:91] offset:512
	global_store_dwordx4 v231, v[90:93], s[90:91] offset:512
	global_store_dwordx4 v244, v[86:89], s[90:91] offset:512
	global_store_dwordx4 v245, v[82:85], s[90:91] offset:512
	global_load_dwordx4 v[130:133], v246, s[90:91]
	global_load_dwordx4 v[134:137], v247, s[90:91]
	global_load_dwordx4 v[138:141], v248, s[90:91]
	global_load_dwordx4 v[142:145], v249, s[90:91]
	v_lshrrev_b32_e32 v148, 1, v246
	v_lshrrev_b32_e32 v156, 9, v246
	v_and_b32_e32 v156, -8, v156
	v_lshrrev_b32_e32 v150, 1, v247
	v_lshrrev_b32_e32 v158, 9, v247
	v_and_b32_e32 v158, -8, v158
	v_lshrrev_b32_e32 v152, 1, v248
	v_lshrrev_b32_e32 v160, 9, v248
	v_and_b32_e32 v160, -8, v160
	v_lshrrev_b32_e32 v154, 1, v249
	v_lshrrev_b32_e32 v162, 9, v249
	v_and_b32_e32 v162, -8, v162
	global_load_dwordx2 v[148:149], v148, s[50:51]
	global_load_dwordx2 v[150:151], v150, s[50:51]
	global_load_dwordx2 v[152:153], v152, s[50:51]
	global_load_dwordx2 v[154:155], v154, s[50:51]
	global_load_dwordx2 v[156:157], v156, s[52:53]
	global_load_dwordx2 v[158:159], v158, s[52:53]
	global_load_dwordx2 v[160:161], v160, s[52:53]
	global_load_dwordx2 v[162:163], v162, s[52:53]
	global_load_dwordx4 v[164:167], v250, s[4:5]
	global_load_dwordx4 v[168:171], v250, s[40:41]
	s_waitcnt vmcnt(18)
; DI float bf_lo(unsigned w) { return __uint_as_float(w << 16); }
; DI float bf_hi(unsigned w) { return __uint_as_float(w & 0xFFFF0000u); }
; #define RES_LOAD(k, s) do { _Pragma("unroll") for (int m = 0; m < 4; ++m) { const int row = row0 + ((k) >> 2) * HALF + m * 16; const size_t o = (size_t)row * 1024 + col0 + (((k) >> 1) & 1) * HALF + ((k) & 1) * 16; \
;             xv[s][m] = *(const f32x4*)(xin + o); if (HAS_T) tv[s][m] = *(const u32x2*)(T + o); if (LNX) sm[s][m] = *(const f32x2*)(stats + 2 * (size_t)row); } } while (0)
;     DI void operator()(const f32x4 (&acc)[2][2][4][2], const Unit& u, int wr, int wc, int fr, int fq) const {
;     ...
; #pragma unroll
;         for (int k = 0; k < 8; ++k) {
;             RES_LOAD(k, k & 1);
;             const int ai = k >> 2, bj = (k >> 1) & 1, n = k & 1;
;             f32x4 gv = {1.f, 1.f, 1.f, 1.f}, bv = {0.f, 0.f, 0.f, 0.f};
;             if (LNX) { gv = *(const f32x4*)(lg + col0 + bj * HALF + n * 16); bv = *(const f32x4*)(lb + col0 + bj * HALF + n * 16); }
; #pragma unroll
;             for (int m = 0; m < 4; ++m) {
;                 const size_t o = o0 + (size_t)(ai * HALF + m * 16) * 1024 + bj * HALF + n * 16;
;                 f32x4 x = xv[k & 1][m];
;                 if (LNX) x = (x - sm[k & 1][m][0]) * sm[k & 1][m][1] * gv + bv;
;                 f32x4 r = acc[ai][bj][m][n] + x * ALPHA;
;                 if (HAS_T) { const u32x2 t = tv[k & 1][m]; r[0] += bf_lo(t.x); r[1] += bf_hi(t.x); r[2] += bf_lo(t.y); r[3] += bf_hi(t.y); }
;                 *(f32x4*)(y + o) = r;
;             }
;         }
	v_sub_f32_e32 v172, v172, v214
	v_sub_f32_e32 v173, v173, v214
	v_sub_f32_e32 v174, v174, v214
	v_sub_f32_e32 v175, v175, v214
	v_pk_mul_f32 v[172:173], v[214:215], v[172:173] op_sel:[1,0]
	v_pk_mul_f32 v[174:175], v[214:215], v[174:175] op_sel:[1,0]
	v_pk_fma_f32 v[172:173], v[172:173], v[222:223], v[226:227]
	v_pk_fma_f32 v[174:175], v[174:175], v[224:225], v[228:229]
	v_pk_fma_f32 v[78:79], v[172:173], s[64:65], v[78:79] op_sel_hi:[1,0,1]
	v_pk_fma_f32 v[80:81], v[174:175], s[64:65], v[80:81] op_sel_hi:[1,0,1]
	v_lshlrev_b32_e32 v172, 16, v188
	v_and_b32_e32 v173, 0xffff0000, v188
	v_lshlrev_b32_e32 v174, 16, v189
	v_and_b32_e32 v175, 0xffff0000, v189
	v_pk_add_f32 v[78:79], v[78:79], v[172:173]
	v_pk_add_f32 v[80:81], v[80:81], v[174:175]
	v_sub_f32_e32 v176, v176, v216
	v_sub_f32_e32 v177, v177, v216
	v_sub_f32_e32 v178, v178, v216
	v_sub_f32_e32 v179, v179, v216
	v_pk_mul_f32 v[176:177], v[216:217], v[176:177] op_sel:[1,0]
	v_pk_mul_f32 v[178:179], v[216:217], v[178:179] op_sel:[1,0]
	v_pk_fma_f32 v[176:177], v[176:177], v[222:223], v[226:227]
	v_pk_fma_f32 v[178:179], v[178:179], v[224:225], v[228:229]
	v_pk_fma_f32 v[74:75], v[176:177], s[64:65], v[74:75] op_sel_hi:[1,0,1]
	v_pk_fma_f32 v[76:77], v[178:179], s[64:65], v[76:77] op_sel_hi:[1,0,1]
	v_lshlrev_b32_e32 v176, 16, v190
	v_and_b32_e32 v177, 0xffff0000, v190
	v_lshlrev_b32_e32 v178, 16, v191
	v_and_b32_e32 v179, 0xffff0000, v191
	v_pk_add_f32 v[74:75], v[74:75], v[176:177]
	v_pk_add_f32 v[76:77], v[76:77], v[178:179]
	v_sub_f32_e32 v180, v180, v218
	v_sub_f32_e32 v181, v181, v218
	v_sub_f32_e32 v182, v182, v218
	v_sub_f32_e32 v183, v183, v218
	v_pk_mul_f32 v[180:181], v[218:219], v[180:181] op_sel:[1,0]
	v_pk_mul_f32 v[182:183], v[218:219], v[182:183] op_sel:[1,0]
	v_pk_fma_f32 v[180:181], v[180:181], v[222:223], v[226:227]
	v_pk_fma_f32 v[182:183], v[182:183], v[224:225], v[228:229]
	v_pk_fma_f32 v[70:71], v[180:181], s[64:65], v[70:71] op_sel_hi:[1,0,1]
	v_pk_fma_f32 v[72:73], v[182:183], s[64:65], v[72:73] op_sel_hi:[1,0,1]
	v_lshlrev_b32_e32 v180, 16, v198
	v_and_b32_e32 v181, 0xffff0000, v198
	v_lshlrev_b32_e32 v182, 16, v199
	v_and_b32_e32 v183, 0xffff0000, v199
	v_pk_add_f32 v[70:71], v[70:71], v[180:181]
	v_pk_add_f32 v[72:73], v[72:73], v[182:183]
	v_sub_f32_e32 v184, v184, v220
	v_sub_f32_e32 v185, v185, v220
	v_sub_f32_e32 v186, v186, v220
	v_sub_f32_e32 v187, v187, v220
	v_pk_mul_f32 v[184:185], v[220:221], v[184:185] op_sel:[1,0]
	v_pk_mul_f32 v[186:187], v[220:221], v[186:187] op_sel:[1,0]
	v_pk_fma_f32 v[184:185], v[184:185], v[222:223], v[226:227]
	v_pk_fma_f32 v[186:187], v[186:187], v[224:225], v[228:229]
	v_pk_fma_f32 v[66:67], v[184:185], s[64:65], v[66:67] op_sel_hi:[1,0,1]
	v_pk_fma_f32 v[68:69], v[186:187], s[64:65], v[68:69] op_sel_hi:[1,0,1]
	v_lshlrev_b32_e32 v184, 16, v200
	v_and_b32_e32 v185, 0xffff0000, v200
	v_lshlrev_b32_e32 v186, 16, v201
	v_and_b32_e32 v187, 0xffff0000, v201
	v_pk_add_f32 v[66:67], v[66:67], v[184:185]
	v_pk_add_f32 v[68:69], v[68:69], v[186:187]
	global_store_dwordx4 v230, v[78:81], s[90:91] offset:576
	global_store_dwordx4 v231, v[74:77], s[90:91] offset:576
	global_store_dwordx4 v244, v[70:73], s[90:91] offset:576
	global_store_dwordx4 v245, v[66:69], s[90:91] offset:576
	global_load_dwordx4 v[172:175], v246, s[90:91] offset:64
	global_load_dwordx4 v[176:179], v247, s[90:91] offset:64
	global_load_dwordx4 v[180:183], v248, s[90:91] offset:64
	global_load_dwordx4 v[184:187], v249, s[90:91] offset:64
	v_lshrrev_b32_e32 v188, 1, v246
	v_lshrrev_b32_e32 v214, 9, v246
	v_and_b32_e32 v214, -8, v214
	v_lshrrev_b32_e32 v190, 1, v247
	v_lshrrev_b32_e32 v216, 9, v247
	v_and_b32_e32 v216, -8, v216
	v_lshrrev_b32_e32 v198, 1, v248
	v_lshrrev_b32_e32 v218, 9, v248
	v_and_b32_e32 v218, -8, v218
	v_lshrrev_b32_e32 v200, 1, v249
	v_lshrrev_b32_e32 v220, 9, v249
	v_and_b32_e32 v220, -8, v220
	global_load_dwordx2 v[188:189], v188, s[50:51] offset:32
	global_load_dwordx2 v[190:191], v190, s[50:51] offset:32
	global_load_dwordx2 v[198:199], v198, s[50:51] offset:32
	global_load_dwordx2 v[200:201], v200, s[50:51] offset:32
	global_load_dwordx2 v[214:215], v214, s[52:53]
	global_load_dwordx2 v[216:217], v216, s[52:53]
	global_load_dwordx2 v[218:219], v218, s[52:53]
	global_load_dwordx2 v[220:221], v220, s[52:53]
	global_load_dwordx4 v[222:225], v250, s[4:5] offset:64
	global_load_dwordx4 v[226:229], v250, s[40:41] offset:64
	s_waitcnt vmcnt(18)
; DI float bf_lo(unsigned w) { return __uint_as_float(w << 16); }
; DI float bf_hi(unsigned w) { return __uint_as_float(w & 0xFFFF0000u); }
; #define RES_LOAD(k, s) do { _Pragma("unroll") for (int m = 0; m < 4; ++m) { const int row = row0 + ((k) >> 2) * HALF + m * 16; const size_t o = (size_t)row * 1024 + col0 + (((k) >> 1) & 1) * HALF + ((k) & 1) * 16; \
;             xv[s][m] = *(const f32x4*)(xin + o); if (HAS_T) tv[s][m] = *(const u32x2*)(T + o); if (LNX) sm[s][m] = *(const f32x2*)(stats + 2 * (size_t)row); } } while (0)
;     DI void operator()(const f32x4 (&acc)[2][2][4][2], const Unit& u, int wr, int wc, int fr, int fq) const {
;     ...
; #pragma unroll
;         for (int k = 0; k < 8; ++k) {
;             RES_LOAD(k, k & 1);
;             const int ai = k >> 2, bj = (k >> 1) & 1, n = k & 1;
;             f32x4 gv = {1.f, 1.f, 1.f, 1.f}, bv = {0.f, 0.f, 0.f, 0.f};
;             if (LNX) { gv = *(const f32x4*)(lg + col0 + bj * HALF + n * 16); bv = *(const f32x4*)(lb + col0 + bj * HALF + n * 16); }
; #pragma unroll
;             for (int m = 0; m < 4; ++m) {
;                 const size_t o = o0 + (size_t)(ai * HALF + m * 16) * 1024 + bj * HALF + n * 16;
;                 f32x4 x = xv[k & 1][m];
;                 if (LNX) x = (x - sm[k & 1][m][0]) * sm[k & 1][m][1] * gv + bv;
;                 f32x4 r = acc[ai][bj][m][n] + x * ALPHA;
;                 if (HAS_T) { const u32x2 t = tv[k & 1][m]; r[0] += bf_lo(t.x); r[1] += bf_hi(t.x); r[2] += bf_lo(t.y); r[3] += bf_hi(t.y); }
;                 *(f32x4*)(y + o) = r;
;             }
;         }
	v_sub_f32_e32 v130, v130, v156
	v_sub_f32_e32 v131, v131, v156
	v_sub_f32_e32 v132, v132, v156
	v_sub_f32_e32 v133, v133, v156
	v_pk_mul_f32 v[130:131], v[156:157], v[130:131] op_sel:[1,0]
	v_pk_mul_f32 v[132:133], v[156:157], v[132:133] op_sel:[1,0]
	v_pk_fma_f32 v[130:131], v[130:131], v[164:165], v[168:169]
	v_pk_fma_f32 v[132:133], v[132:133], v[166:167], v[170:171]
	v_pk_fma_f32 v[62:63], v[130:131], s[64:65], v[62:63] op_sel_hi:[1,0,1]
	v_pk_fma_f32 v[64:65], v[132:133], s[64:65], v[64:65] op_sel_hi:[1,0,1]
	v_lshlrev_b32_e32 v130, 16, v148
	v_and_b32_e32 v131, 0xffff0000, v148
	v_lshlrev_b32_e32 v132, 16, v149
	v_and_b32_e32 v133, 0xffff0000, v149
	v_pk_add_f32 v[62:63], v[62:63], v[130:131]
	v_pk_add_f32 v[64:65], v[64:65], v[132:133]
	v_sub_f32_e32 v134, v134, v158
	v_sub_f32_e32 v135, v135, v158
	v_sub_f32_e32 v136, v136, v158
	v_sub_f32_e32 v137, v137, v158
	v_pk_mul_f32 v[134:135], v[158:159], v[134:135] op_sel:[1,0]
	v_pk_mul_f32 v[136:137], v[158:159], v[136:137] op_sel:[1,0]
	v_pk_fma_f32 v[134:135], v[134:135], v[164:165], v[168:169]
	v_pk_fma_f32 v[136:137], v[136:137], v[166:167], v[170:171]
	v_pk_fma_f32 v[58:59], v[134:135], s[64:65], v[58:59] op_sel_hi:[1,0,1]
	v_pk_fma_f32 v[60:61], v[136:137], s[64:65], v[60:61] op_sel_hi:[1,0,1]
	v_lshlrev_b32_e32 v134, 16, v150
	v_and_b32_e32 v135, 0xffff0000, v150
	v_lshlrev_b32_e32 v136, 16, v151
	v_and_b32_e32 v137, 0xffff0000, v151
	v_pk_add_f32 v[58:59], v[58:59], v[134:135]
	v_pk_add_f32 v[60:61], v[60:61], v[136:137]
	v_sub_f32_e32 v138, v138, v160
	v_sub_f32_e32 v139, v139, v160
	v_sub_f32_e32 v140, v140, v160
	v_sub_f32_e32 v141, v141, v160
	v_pk_mul_f32 v[138:139], v[160:161], v[138:139] op_sel:[1,0]
	v_pk_mul_f32 v[140:141], v[160:161], v[140:141] op_sel:[1,0]
	v_pk_fma_f32 v[138:139], v[138:139], v[164:165], v[168:169]
	v_pk_fma_f32 v[140:141], v[140:141], v[166:167], v[170:171]
	v_pk_fma_f32 v[54:55], v[138:139], s[64:65], v[54:55] op_sel_hi:[1,0,1]
	v_pk_fma_f32 v[56:57], v[140:141], s[64:65], v[56:57] op_sel_hi:[1,0,1]
	v_lshlrev_b32_e32 v138, 16, v152
	v_and_b32_e32 v139, 0xffff0000, v152
	v_lshlrev_b32_e32 v140, 16, v153
	v_and_b32_e32 v141, 0xffff0000, v153
	v_pk_add_f32 v[54:55], v[54:55], v[138:139]
	v_pk_add_f32 v[56:57], v[56:57], v[140:141]
	v_sub_f32_e32 v142, v142, v162
	v_sub_f32_e32 v143, v143, v162
	v_sub_f32_e32 v144, v144, v162
	v_sub_f32_e32 v145, v145, v162
	v_pk_mul_f32 v[142:143], v[162:163], v[142:143] op_sel:[1,0]
	v_pk_mul_f32 v[144:145], v[162:163], v[144:145] op_sel:[1,0]
	v_pk_fma_f32 v[142:143], v[142:143], v[164:165], v[168:169]
	v_pk_fma_f32 v[144:145], v[144:145], v[166:167], v[170:171]
	v_pk_fma_f32 v[50:51], v[142:143], s[64:65], v[50:51] op_sel_hi:[1,0,1]
	v_pk_fma_f32 v[52:53], v[144:145], s[64:65], v[52:53] op_sel_hi:[1,0,1]
	v_lshlrev_b32_e32 v142, 16, v154
	v_and_b32_e32 v143, 0xffff0000, v154
	v_lshlrev_b32_e32 v144, 16, v155
	v_and_b32_e32 v145, 0xffff0000, v155
	v_pk_add_f32 v[50:51], v[50:51], v[142:143]
	v_pk_add_f32 v[52:53], v[52:53], v[144:145]
	global_store_dwordx4 v246, v[62:65], s[90:91]
	global_store_dwordx4 v247, v[58:61], s[90:91]
	global_store_dwordx4 v248, v[54:57], s[90:91]
	global_store_dwordx4 v249, v[50:53], s[90:91]
	global_load_dwordx4 v[130:133], v246, s[90:91] offset:512
	global_load_dwordx4 v[134:137], v247, s[90:91] offset:512
	global_load_dwordx4 v[138:141], v248, s[90:91] offset:512
	global_load_dwordx4 v[142:145], v249, s[90:91] offset:512
	v_lshrrev_b32_e32 v148, 1, v246
	v_lshrrev_b32_e32 v156, 9, v246
	v_and_b32_e32 v156, -8, v156
	v_lshrrev_b32_e32 v150, 1, v247
	v_lshrrev_b32_e32 v158, 9, v247
	v_and_b32_e32 v158, -8, v158
	v_lshrrev_b32_e32 v152, 1, v248
	v_lshrrev_b32_e32 v160, 9, v248
	v_and_b32_e32 v160, -8, v160
	v_lshrrev_b32_e32 v154, 1, v249
	v_lshrrev_b32_e32 v162, 9, v249
	v_and_b32_e32 v162, -8, v162
	global_load_dwordx2 v[148:149], v148, s[50:51] offset:256
	global_load_dwordx2 v[150:151], v150, s[50:51] offset:256
	global_load_dwordx2 v[152:153], v152, s[50:51] offset:256
	global_load_dwordx2 v[154:155], v154, s[50:51] offset:256
	global_load_dwordx2 v[156:157], v156, s[52:53]
	global_load_dwordx2 v[158:159], v158, s[52:53]
	global_load_dwordx2 v[160:161], v160, s[52:53]
	global_load_dwordx2 v[162:163], v162, s[52:53]
	global_load_dwordx4 v[164:167], v250, s[4:5] offset:512
	global_load_dwordx4 v[168:171], v250, s[40:41] offset:512
	s_waitcnt vmcnt(18)
; DI float bf_lo(unsigned w) { return __uint_as_float(w << 16); }
; DI float bf_hi(unsigned w) { return __uint_as_float(w & 0xFFFF0000u); }
; #define RES_LOAD(k, s) do { _Pragma("unroll") for (int m = 0; m < 4; ++m) { const int row = row0 + ((k) >> 2) * HALF + m * 16; const size_t o = (size_t)row * 1024 + col0 + (((k) >> 1) & 1) * HALF + ((k) & 1) * 16; \
;             xv[s][m] = *(const f32x4*)(xin + o); if (HAS_T) tv[s][m] = *(const u32x2*)(T + o); if (LNX) sm[s][m] = *(const f32x2*)(stats + 2 * (size_t)row); } } while (0)
;     DI void operator()(const f32x4 (&acc)[2][2][4][2], const Unit& u, int wr, int wc, int fr, int fq) const {
;     ...
; #pragma unroll
;         for (int k = 0; k < 8; ++k) {
;             RES_LOAD(k, k & 1);
;             const int ai = k >> 2, bj = (k >> 1) & 1, n = k & 1;
;             f32x4 gv = {1.f, 1.f, 1.f, 1.f}, bv = {0.f, 0.f, 0.f, 0.f};
;             if (LNX) { gv = *(const f32x4*)(lg + col0 + bj * HALF + n * 16); bv = *(const f32x4*)(lb + col0 + bj * HALF + n * 16); }
; #pragma unroll
;             for (int m = 0; m < 4; ++m) {
;                 const size_t o = o0 + (size_t)(ai * HALF + m * 16) * 1024 + bj * HALF + n * 16;
;                 f32x4 x = xv[k & 1][m];
;                 if (LNX) x = (x - sm[k & 1][m][0]) * sm[k & 1][m][1] * gv + bv;
;                 f32x4 r = acc[ai][bj][m][n] + x * ALPHA;
;                 if (HAS_T) { const u32x2 t = tv[k & 1][m]; r[0] += bf_lo(t.x); r[1] += bf_hi(t.x); r[2] += bf_lo(t.y); r[3] += bf_hi(t.y); }
;                 *(f32x4*)(y + o) = r;
;             }
;         }
	v_sub_f32_e32 v172, v172, v214
	v_sub_f32_e32 v173, v173, v214
	v_sub_f32_e32 v174, v174, v214
	v_sub_f32_e32 v175, v175, v214
	v_pk_mul_f32 v[172:173], v[214:215], v[172:173] op_sel:[1,0]
	v_pk_mul_f32 v[174:175], v[214:215], v[174:175] op_sel:[1,0]
	v_pk_fma_f32 v[172:173], v[172:173], v[222:223], v[226:227]
	v_pk_fma_f32 v[174:175], v[174:175], v[224:225], v[228:229]
	v_pk_fma_f32 v[46:47], v[172:173], s[64:65], v[46:47] op_sel_hi:[1,0,1]
	v_pk_fma_f32 v[48:49], v[174:175], s[64:65], v[48:49] op_sel_hi:[1,0,1]
	v_lshlrev_b32_e32 v172, 16, v188
	v_and_b32_e32 v173, 0xffff0000, v188
	v_lshlrev_b32_e32 v174, 16, v189
	v_and_b32_e32 v175, 0xffff0000, v189
	v_pk_add_f32 v[46:47], v[46:47], v[172:173]
	v_pk_add_f32 v[48:49], v[48:49], v[174:175]
	v_sub_f32_e32 v176, v176, v216
	v_sub_f32_e32 v177, v177, v216
	v_sub_f32_e32 v178, v178, v216
	v_sub_f32_e32 v179, v179, v216
	v_pk_mul_f32 v[176:177], v[216:217], v[176:177] op_sel:[1,0]
	v_pk_mul_f32 v[178:179], v[216:217], v[178:179] op_sel:[1,0]
	v_pk_fma_f32 v[176:177], v[176:177], v[222:223], v[226:227]
	v_pk_fma_f32 v[178:179], v[178:179], v[224:225], v[228:229]
	v_pk_fma_f32 v[42:43], v[176:177], s[64:65], v[42:43] op_sel_hi:[1,0,1]
	v_pk_fma_f32 v[44:45], v[178:179], s[64:65], v[44:45] op_sel_hi:[1,0,1]
	v_lshlrev_b32_e32 v176, 16, v190
	v_and_b32_e32 v177, 0xffff0000, v190
	v_lshlrev_b32_e32 v178, 16, v191
	v_and_b32_e32 v179, 0xffff0000, v191
	v_pk_add_f32 v[42:43], v[42:43], v[176:177]
	v_pk_add_f32 v[44:45], v[44:45], v[178:179]
	v_sub_f32_e32 v180, v180, v218
	v_sub_f32_e32 v181, v181, v218
	v_sub_f32_e32 v182, v182, v218
	v_sub_f32_e32 v183, v183, v218
	v_pk_mul_f32 v[180:181], v[218:219], v[180:181] op_sel:[1,0]
	v_pk_mul_f32 v[182:183], v[218:219], v[182:183] op_sel:[1,0]
	v_pk_fma_f32 v[180:181], v[180:181], v[222:223], v[226:227]
	v_pk_fma_f32 v[182:183], v[182:183], v[224:225], v[228:229]
	v_pk_fma_f32 v[38:39], v[180:181], s[64:65], v[38:39] op_sel_hi:[1,0,1]
	v_pk_fma_f32 v[40:41], v[182:183], s[64:65], v[40:41] op_sel_hi:[1,0,1]
	v_lshlrev_b32_e32 v180, 16, v198
	v_and_b32_e32 v181, 0xffff0000, v198
	v_lshlrev_b32_e32 v182, 16, v199
	v_and_b32_e32 v183, 0xffff0000, v199
	v_pk_add_f32 v[38:39], v[38:39], v[180:181]
	v_pk_add_f32 v[40:41], v[40:41], v[182:183]
	v_sub_f32_e32 v184, v184, v220
	v_sub_f32_e32 v185, v185, v220
	v_sub_f32_e32 v186, v186, v220
	v_sub_f32_e32 v187, v187, v220
	v_pk_mul_f32 v[184:185], v[220:221], v[184:185] op_sel:[1,0]
	v_pk_mul_f32 v[186:187], v[220:221], v[186:187] op_sel:[1,0]
	v_pk_fma_f32 v[184:185], v[184:185], v[222:223], v[226:227]
	v_pk_fma_f32 v[186:187], v[186:187], v[224:225], v[228:229]
	v_pk_fma_f32 v[34:35], v[184:185], s[64:65], v[34:35] op_sel_hi:[1,0,1]
	v_pk_fma_f32 v[36:37], v[186:187], s[64:65], v[36:37] op_sel_hi:[1,0,1]
	v_lshlrev_b32_e32 v184, 16, v200
	v_and_b32_e32 v185, 0xffff0000, v200
	v_lshlrev_b32_e32 v186, 16, v201
	v_and_b32_e32 v187, 0xffff0000, v201
	v_pk_add_f32 v[34:35], v[34:35], v[184:185]
	v_pk_add_f32 v[36:37], v[36:37], v[186:187]
	global_store_dwordx4 v246, v[46:49], s[90:91] offset:64
	global_store_dwordx4 v247, v[42:45], s[90:91] offset:64
	global_store_dwordx4 v248, v[38:41], s[90:91] offset:64
	global_store_dwordx4 v249, v[34:37], s[90:91] offset:64
	global_load_dwordx4 v[172:175], v246, s[90:91] offset:576
	global_load_dwordx4 v[176:179], v247, s[90:91] offset:576
	global_load_dwordx4 v[180:183], v248, s[90:91] offset:576
	global_load_dwordx4 v[184:187], v249, s[90:91] offset:576
	v_lshrrev_b32_e32 v188, 1, v246
	v_lshrrev_b32_e32 v214, 9, v246
	v_and_b32_e32 v214, -8, v214
	v_lshrrev_b32_e32 v190, 1, v247
	v_lshrrev_b32_e32 v216, 9, v247
	v_and_b32_e32 v216, -8, v216
	v_lshrrev_b32_e32 v198, 1, v248
	v_lshrrev_b32_e32 v218, 9, v248
	v_and_b32_e32 v218, -8, v218
	v_lshrrev_b32_e32 v200, 1, v249
	v_lshrrev_b32_e32 v220, 9, v249
	v_and_b32_e32 v220, -8, v220
	global_load_dwordx2 v[188:189], v188, s[50:51] offset:288
	global_load_dwordx2 v[190:191], v190, s[50:51] offset:288
	global_load_dwordx2 v[198:199], v198, s[50:51] offset:288
	global_load_dwordx2 v[200:201], v200, s[50:51] offset:288
	global_load_dwordx2 v[214:215], v214, s[52:53]
	global_load_dwordx2 v[216:217], v216, s[52:53]
	global_load_dwordx2 v[218:219], v218, s[52:53]
	global_load_dwordx2 v[220:221], v220, s[52:53]
	global_load_dwordx4 v[222:225], v250, s[4:5] offset:576
	global_load_dwordx4 v[226:229], v250, s[40:41] offset:576
	s_waitcnt vmcnt(18)
; DI float bf_lo(unsigned w) { return __uint_as_float(w << 16); }
; DI float bf_hi(unsigned w) { return __uint_as_float(w & 0xFFFF0000u); }
; #define RES_LOAD(k, s) do { _Pragma("unroll") for (int m = 0; m < 4; ++m) { const int row = row0 + ((k) >> 2) * HALF + m * 16; const size_t o = (size_t)row * 1024 + col0 + (((k) >> 1) & 1) * HALF + ((k) & 1) * 16; \
;             xv[s][m] = *(const f32x4*)(xin + o); if (HAS_T) tv[s][m] = *(const u32x2*)(T + o); if (LNX) sm[s][m] = *(const f32x2*)(stats + 2 * (size_t)row); } } while (0)
;     DI void operator()(const f32x4 (&acc)[2][2][4][2], const Unit& u, int wr, int wc, int fr, int fq) const {
;     ...
;         for (int k = 0; k < 8; ++k) {
;             RES_LOAD(k, k & 1);
;             const int ai = k >> 2, bj = (k >> 1) & 1, n = k & 1;
;             f32x4 gv = {1.f, 1.f, 1.f, 1.f}, bv = {0.f, 0.f, 0.f, 0.f};
;             if (LNX) { gv = *(const f32x4*)(lg + col0 + bj * HALF + n * 16); bv = *(const f32x4*)(lb + col0 + bj * HALF + n * 16); }
; #pragma unroll
;             for (int m = 0; m < 4; ++m) {
;                 const size_t o = o0 + (size_t)(ai * HALF + m * 16) * 1024 + bj * HALF + n * 16;
;                 f32x4 x = xv[k & 1][m];
;                 if (LNX) x = (x - sm[k & 1][m][0]) * sm[k & 1][m][1] * gv + bv;
;                 f32x4 r = acc[ai][bj][m][n] + x * ALPHA;
;                 if (HAS_T) { const u32x2 t = tv[k & 1][m]; r[0] += bf_lo(t.x); r[1] += bf_hi(t.x); r[2] += bf_lo(t.y); r[3] += bf_hi(t.y); }
;                 *(f32x4*)(y + o) = r;
;             }
;         }
; template <class Epi, class Sched>
; DI void gemm_phase(LAS unsigned char* lds, const Gemm g, const Sched& S, const Epi& E, const int tid) {
;     ...
;         E(acc, cur, wr, wc, fr, fq);
;         if (!has_next) break;
; #pragma unroll
;         for (int a = 0; a < 2; ++a)
; #pragma unroll
;             for (int b = 0; b < 2; ++b)
; #pragma unroll
;                 for (int m = 0; m < 4; ++m)
; #pragma unroll
;                     for (int n = 0; n < 2; ++n) acc[a][b][m][n] = (f32x4){0.f, 0.f, 0.f, 0.f};
;         cur = nxt; cA = nA; cB = nB; ++ui;
	v_sub_f32_e32 v130, v130, v156
	v_sub_f32_e32 v131, v131, v156
	v_sub_f32_e32 v132, v132, v156
	v_sub_f32_e32 v133, v133, v156
	v_pk_mul_f32 v[130:131], v[156:157], v[130:131] op_sel:[1,0]
	v_pk_mul_f32 v[132:133], v[156:157], v[132:133] op_sel:[1,0]
	v_pk_fma_f32 v[130:131], v[130:131], v[164:165], v[168:169]
	v_pk_fma_f32 v[132:133], v[132:133], v[166:167], v[170:171]
	v_pk_fma_f32 v[30:31], v[130:131], s[64:65], v[30:31] op_sel_hi:[1,0,1]
	v_pk_fma_f32 v[32:33], v[132:133], s[64:65], v[32:33] op_sel_hi:[1,0,1]
	v_lshlrev_b32_e32 v130, 16, v148
	v_and_b32_e32 v131, 0xffff0000, v148
	v_lshlrev_b32_e32 v132, 16, v149
	v_and_b32_e32 v133, 0xffff0000, v149
	v_pk_add_f32 v[30:31], v[30:31], v[130:131]
	v_pk_add_f32 v[32:33], v[32:33], v[132:133]
	v_sub_f32_e32 v134, v134, v158
	v_sub_f32_e32 v135, v135, v158
	v_sub_f32_e32 v136, v136, v158
	v_sub_f32_e32 v137, v137, v158
	v_pk_mul_f32 v[134:135], v[158:159], v[134:135] op_sel:[1,0]
	v_pk_mul_f32 v[136:137], v[158:159], v[136:137] op_sel:[1,0]
	v_pk_fma_f32 v[134:135], v[134:135], v[164:165], v[168:169]
	v_pk_fma_f32 v[136:137], v[136:137], v[166:167], v[170:171]
	v_pk_fma_f32 v[26:27], v[134:135], s[64:65], v[26:27] op_sel_hi:[1,0,1]
	v_pk_fma_f32 v[28:29], v[136:137], s[64:65], v[28:29] op_sel_hi:[1,0,1]
	v_lshlrev_b32_e32 v134, 16, v150
	v_and_b32_e32 v135, 0xffff0000, v150
	v_lshlrev_b32_e32 v136, 16, v151
	v_and_b32_e32 v137, 0xffff0000, v151
	v_pk_add_f32 v[26:27], v[26:27], v[134:135]
	v_pk_add_f32 v[28:29], v[28:29], v[136:137]
	v_sub_f32_e32 v138, v138, v160
	v_sub_f32_e32 v139, v139, v160
	v_sub_f32_e32 v140, v140, v160
	v_sub_f32_e32 v141, v141, v160
	v_pk_mul_f32 v[138:139], v[160:161], v[138:139] op_sel:[1,0]
	v_pk_mul_f32 v[140:141], v[160:161], v[140:141] op_sel:[1,0]
	v_pk_fma_f32 v[138:139], v[138:139], v[164:165], v[168:169]
	v_pk_fma_f32 v[140:141], v[140:141], v[166:167], v[170:171]
	v_pk_fma_f32 v[22:23], v[138:139], s[64:65], v[22:23] op_sel_hi:[1,0,1]
	v_pk_fma_f32 v[24:25], v[140:141], s[64:65], v[24:25] op_sel_hi:[1,0,1]
	v_lshlrev_b32_e32 v138, 16, v152
	v_and_b32_e32 v139, 0xffff0000, v152
	v_lshlrev_b32_e32 v140, 16, v153
	v_and_b32_e32 v141, 0xffff0000, v153
	v_pk_add_f32 v[22:23], v[22:23], v[138:139]
	v_pk_add_f32 v[24:25], v[24:25], v[140:141]
	v_sub_f32_e32 v142, v142, v162
	v_sub_f32_e32 v143, v143, v162
	v_sub_f32_e32 v144, v144, v162
	v_sub_f32_e32 v145, v145, v162
	v_pk_mul_f32 v[142:143], v[162:163], v[142:143] op_sel:[1,0]
	v_pk_mul_f32 v[144:145], v[162:163], v[144:145] op_sel:[1,0]
	v_pk_fma_f32 v[142:143], v[142:143], v[164:165], v[168:169]
	v_pk_fma_f32 v[144:145], v[144:145], v[166:167], v[170:171]
	v_pk_fma_f32 v[18:19], v[142:143], s[64:65], v[18:19] op_sel_hi:[1,0,1]
	v_pk_fma_f32 v[20:21], v[144:145], s[64:65], v[20:21] op_sel_hi:[1,0,1]
	v_lshlrev_b32_e32 v142, 16, v154
	v_and_b32_e32 v143, 0xffff0000, v154
	v_lshlrev_b32_e32 v144, 16, v155
	v_and_b32_e32 v145, 0xffff0000, v155
	v_pk_add_f32 v[18:19], v[18:19], v[142:143]
	v_pk_add_f32 v[20:21], v[20:21], v[144:145]
	global_store_dwordx4 v246, v[30:33], s[90:91] offset:512
	global_store_dwordx4 v247, v[26:29], s[90:91] offset:512
	global_store_dwordx4 v248, v[22:25], s[90:91] offset:512
	global_store_dwordx4 v249, v[18:21], s[90:91] offset:512
	s_waitcnt vmcnt(4)
	v_sub_f32_e32 v172, v172, v214
	v_sub_f32_e32 v173, v173, v214
	v_sub_f32_e32 v174, v174, v214
	v_sub_f32_e32 v175, v175, v214
	v_pk_mul_f32 v[172:173], v[214:215], v[172:173] op_sel:[1,0]
	v_pk_mul_f32 v[174:175], v[214:215], v[174:175] op_sel:[1,0]
	v_pk_fma_f32 v[172:173], v[172:173], v[222:223], v[226:227]
	v_pk_fma_f32 v[174:175], v[174:175], v[224:225], v[228:229]
	v_pk_fma_f32 v[14:15], v[172:173], s[64:65], v[14:15] op_sel_hi:[1,0,1]
	v_pk_fma_f32 v[16:17], v[174:175], s[64:65], v[16:17] op_sel_hi:[1,0,1]
	v_lshlrev_b32_e32 v172, 16, v188
	v_and_b32_e32 v173, 0xffff0000, v188
	v_lshlrev_b32_e32 v174, 16, v189
	v_and_b32_e32 v175, 0xffff0000, v189
	v_pk_add_f32 v[14:15], v[14:15], v[172:173]
	v_pk_add_f32 v[16:17], v[16:17], v[174:175]
	v_sub_f32_e32 v176, v176, v216
	v_sub_f32_e32 v177, v177, v216
	v_sub_f32_e32 v178, v178, v216
	v_sub_f32_e32 v179, v179, v216
	v_pk_mul_f32 v[176:177], v[216:217], v[176:177] op_sel:[1,0]
	v_pk_mul_f32 v[178:179], v[216:217], v[178:179] op_sel:[1,0]
	v_pk_fma_f32 v[176:177], v[176:177], v[222:223], v[226:227]
	v_pk_fma_f32 v[178:179], v[178:179], v[224:225], v[228:229]
	v_pk_fma_f32 v[10:11], v[176:177], s[64:65], v[10:11] op_sel_hi:[1,0,1]
	v_pk_fma_f32 v[12:13], v[178:179], s[64:65], v[12:13] op_sel_hi:[1,0,1]
	v_lshlrev_b32_e32 v176, 16, v190
	v_and_b32_e32 v177, 0xffff0000, v190
	v_lshlrev_b32_e32 v178, 16, v191
	v_and_b32_e32 v179, 0xffff0000, v191
	v_pk_add_f32 v[10:11], v[10:11], v[176:177]
	v_pk_add_f32 v[12:13], v[12:13], v[178:179]
	v_sub_f32_e32 v180, v180, v218
	v_sub_f32_e32 v181, v181, v218
	v_sub_f32_e32 v182, v182, v218
	v_sub_f32_e32 v183, v183, v218
	v_pk_mul_f32 v[180:181], v[218:219], v[180:181] op_sel:[1,0]
	v_pk_mul_f32 v[182:183], v[218:219], v[182:183] op_sel:[1,0]
	v_pk_fma_f32 v[180:181], v[180:181], v[222:223], v[226:227]
	v_pk_fma_f32 v[182:183], v[182:183], v[224:225], v[228:229]
	v_pk_fma_f32 v[6:7], v[180:181], s[64:65], v[6:7] op_sel_hi:[1,0,1]
	v_pk_fma_f32 v[8:9], v[182:183], s[64:65], v[8:9] op_sel_hi:[1,0,1]
	v_lshlrev_b32_e32 v180, 16, v198
	v_and_b32_e32 v181, 0xffff0000, v198
	v_lshlrev_b32_e32 v182, 16, v199
	v_and_b32_e32 v183, 0xffff0000, v199
	v_pk_add_f32 v[6:7], v[6:7], v[180:181]
	v_pk_add_f32 v[8:9], v[8:9], v[182:183]
	v_sub_f32_e32 v184, v184, v220
	v_sub_f32_e32 v185, v185, v220
	v_sub_f32_e32 v186, v186, v220
	v_sub_f32_e32 v187, v187, v220
	v_pk_mul_f32 v[184:185], v[220:221], v[184:185] op_sel:[1,0]
	v_pk_mul_f32 v[186:187], v[220:221], v[186:187] op_sel:[1,0]
	v_pk_fma_f32 v[184:185], v[184:185], v[222:223], v[226:227]
	v_pk_fma_f32 v[186:187], v[186:187], v[224:225], v[228:229]
	v_pk_fma_f32 v[2:3], v[184:185], s[64:65], v[2:3] op_sel_hi:[1,0,1]
	v_pk_fma_f32 v[4:5], v[186:187], s[64:65], v[4:5] op_sel_hi:[1,0,1]
	v_lshlrev_b32_e32 v184, 16, v200
	v_and_b32_e32 v185, 0xffff0000, v200
	v_lshlrev_b32_e32 v186, 16, v201
	v_and_b32_e32 v187, 0xffff0000, v201
	v_pk_add_f32 v[2:3], v[2:3], v[184:185]
	v_pk_add_f32 v[4:5], v[4:5], v[186:187]
	global_store_dwordx4 v246, v[14:17], s[90:91] offset:576
	global_store_dwordx4 v247, v[10:13], s[90:91] offset:576
	global_store_dwordx4 v248, v[6:9], s[90:91] offset:576
	global_store_dwordx4 v249, v[2:5], s[90:91] offset:576
	s_mov_b64 s[52:53], s[48:49]
	s_mov_b64 s[50:51], s[46:47]
	s_mov_b32 s64, s42
	s_mov_b32 s65, s44
	s_and_b64 vcc, exec, s[38:39]
	s_cbranch_vccz .LBB0_21
	s_waitcnt vmcnt(0)
	v_readlane_b32 s76, v255, 15
	v_readlane_b32 s78, v255, 17
	s_cmpk_gt_u32 s2, 0xff
	v_readlane_b32 s77, v255, 16
	v_readlane_b32 s79, v255, 18
	s_mov_b64 s[44:45], s[8:9]
	s_cbranch_scc1 .LBB0_32
	s_barrier
